# K-loop: post-MMA barrier moved 4 MFMAs earlier with s_setprio 3 on the tail MFMAs (covers barrier latency); plus P2 epilogue prefetch
# speedup vs baseline: 1.0052x; 1.0052x over previous
; #define PG8_STAGE(bufoff, gbase, voff) do { _Pragma("unroll") for (int _i = 0; _i < 2; ++_i) \
;         __builtin_amdgcn_global_load_lds((const unsigned*)((const char*)(gbase) + (voff)[_i]), (PG8_LAS unsigned*)(lds + (bufoff) + ldsw + _i * 8192), 16, 0, 0); } while (0)
; #define PG8_LDA(dst, b, h) do { _Pragma("unroll") for (int m = 0; m < 4; ++m) _Pragma("unroll") for (int k = 0; k < 2; ++k) dst[m][k] = *(const PG8_LAS bf16x8*)(lds + PG8_SA(b, h) + aoff + m * 2048 + k * 1024); } while (0)
; #define PG8_LDB(dst, b, h) do { _Pragma("unroll") for (int n = 0; n < 2; ++n) _Pragma("unroll") for (int k = 0; k < 2; ++k) dst[n][k] = *(const PG8_LAS bf16x8*)(lds + PG8_SB(b, h) + boff + n * 2048 + k * 1024); } while (0)
; #define PG8_MMA(ai, bj, At, Bt) do { __builtin_amdgcn_s_setprio(1); _Pragma("unroll") for (int m = 0; m < 4; ++m) _Pragma("unroll") for (int n = 0; n < 2; ++n) _Pragma("unroll") for (int k = 0; k < 2; ++k) \
;         acc[ai][bj][m][n] = __builtin_amdgcn_mfma_f32_16x16x32_bf16(Bt[n][k], At[m][k], acc[ai][bj][m][n], 0, 0, 0); __builtin_amdgcn_s_setprio(0); } while (0)
; #define PG8_WAIT_V(n) asm volatile("s_waitcnt vmcnt(" #n ")" ::: "memory")
; #define PG8_WAIT_L(n) asm volatile("s_waitcnt lgkmcnt(" #n ")" ::: "memory")
; #define PG8_BAR __builtin_amdgcn_s_barrier()
; #define PG8_SCHED __builtin_amdgcn_sched_barrier(0)
; template <class Epi, class Sched, bool ALIGN_EPI = false, bool SP2 = false>
; __device__ __forceinline__ void gemm_phase(PG8_LAS unsigned char* lds, const Gemm g, const Sched& S, const Epi& E, int wave_in) {
;     ...
;             const bool last = (t == nt - 2);
;             const char* a1 = cA + (size_t)(t + 1) * kstep;
;             const char* a2 = last ? nA : cA + (size_t)(t + 2) * kstep; const char* b2 = last ? nB : cB + (size_t)(t + 2) * kstep;
;             const char* a3 = a2 + kstep; const char* b3 = b2 + kstep;
;             if (last && has_next) S.a_ready(nxt);
;             if constexpr (SP2) {
;             PG8_LDB(B0, 0, 0); PG8_LDB(B1, 0, 1); PG8_SCHED; PG8_LDA(At, 0, 0); PG8_STAGE(PG8_SA(1, 1), a1 + hstep, voffA);
;             PG8_WAIT_V(8); PG8_WAIT_L(0); PG8_BAR; PG8_MMA(0, 0, At, B0); PG8_MMA(0, 1, At, B1); PG8_BAR; PG8_SCHED;
;             PG8_LDA(At, 0, 1); PG8_STAGE(PG8_SB(0, 0), b2, voffB); PG8_STAGE(PG8_SB(0, 1), b2 + hstep, voffB); PG8_STAGE(PG8_SA(0, 0), a2, voffA);
.LBB0_184:
	ds_read_b128 v[144:147], v151
	ds_read_b128 v[154:157], v151 offset:1024
	ds_read_b128 v[158:161], v151 offset:2048
	ds_read_b128 v[162:165], v151 offset:3072
	ds_read_b128 v[168:171], v152
	ds_read_b128 v[172:175], v152 offset:1024
	ds_read_b128 v[176:179], v152 offset:2048
	ds_read_b128 v[180:183], v152 offset:3072
	s_add_u32 s34, s30, 0xfff80080
	s_addc_u32 s35, s31, -1
	s_cmp_eq_u32 s55, 28
	s_cselect_b32 s37, s23, s35
	s_cselect_b32 s36, s50, s34
	s_cselect_b32 s35, s19, s53
	s_cselect_b32 s34, s51, s52
	v_lshl_add_u64 v[166:167], s[30:31], 0, v[136:137]
	s_add_i32 m0, s29, 0xc000
	ds_read_b128 v[184:187], v153
	ds_read_b128 v[188:191], v153 offset:1024
	ds_read_b128 v[192:195], v153 offset:2048
	ds_read_b128 v[196:199], v153 offset:3072
	ds_read_b128 v[200:203], v153 offset:4096
	ds_read_b128 v[204:207], v153 offset:5120
	ds_read_b128 v[208:211], v153 offset:6144
	ds_read_b128 v[212:215], v153 offset:7168
	global_load_lds_dwordx4 v[166:167], off
	v_lshl_add_u64 v[166:167], s[30:31], 0, v[138:139]
	s_add_i32 m0, s29, 0xe000
	s_nop 0
	global_load_lds_dwordx4 v[166:167], off
	s_waitcnt vmcnt(8)
	s_waitcnt lgkmcnt(0)
	s_barrier
	s_setprio 1
	s_waitcnt lgkmcnt(0)
	v_mfma_f32_16x16x32_bf16 v[124:127], v[144:147], v[184:187], v[124:127]
	v_mfma_f32_16x16x32_bf16 v[120:123], v[158:161], v[184:187], v[120:123]
	v_mfma_f32_16x16x32_bf16 v[108:111], v[144:147], v[192:195], v[108:111]
	v_mfma_f32_16x16x32_bf16 v[104:107], v[158:161], v[192:195], v[104:107]
	v_mfma_f32_16x16x32_bf16 v[92:95], v[144:147], v[200:203], v[92:95]
	v_mfma_f32_16x16x32_bf16 v[88:91], v[158:161], v[200:203], v[88:91]
	v_mfma_f32_16x16x32_bf16 v[76:79], v[144:147], v[208:211], v[76:79]
	v_mfma_f32_16x16x32_bf16 v[72:75], v[158:161], v[208:211], v[72:75]
	v_mfma_f32_16x16x32_bf16 v[124:127], v[154:157], v[188:191], v[124:127]
	v_mfma_f32_16x16x32_bf16 v[120:123], v[162:165], v[188:191], v[120:123]
	v_mfma_f32_16x16x32_bf16 v[108:111], v[154:157], v[196:199], v[108:111]
	v_mfma_f32_16x16x32_bf16 v[104:107], v[162:165], v[196:199], v[104:107]
	v_mfma_f32_16x16x32_bf16 v[92:95], v[154:157], v[204:207], v[92:95]
	v_mfma_f32_16x16x32_bf16 v[88:91], v[162:165], v[204:207], v[88:91]
	v_mfma_f32_16x16x32_bf16 v[76:79], v[154:157], v[212:215], v[76:79]
	v_mfma_f32_16x16x32_bf16 v[72:75], v[162:165], v[212:215], v[72:75]
	s_setprio 0
	s_setprio 1
	v_mfma_f32_16x16x32_bf16 v[116:119], v[168:171], v[184:187], v[116:119]
	v_mfma_f32_16x16x32_bf16 v[112:115], v[176:179], v[184:187], v[112:115]
	v_mfma_f32_16x16x32_bf16 v[100:103], v[168:171], v[192:195], v[100:103]
	v_mfma_f32_16x16x32_bf16 v[96:99], v[176:179], v[192:195], v[96:99]
	v_mfma_f32_16x16x32_bf16 v[84:87], v[168:171], v[200:203], v[84:87]
	v_mfma_f32_16x16x32_bf16 v[80:83], v[176:179], v[200:203], v[80:83]
	v_mfma_f32_16x16x32_bf16 v[68:71], v[168:171], v[208:211], v[68:71]
	v_mfma_f32_16x16x32_bf16 v[64:67], v[176:179], v[208:211], v[64:67]
	v_mfma_f32_16x16x32_bf16 v[116:119], v[172:175], v[188:191], v[116:119]
	v_mfma_f32_16x16x32_bf16 v[112:115], v[180:183], v[188:191], v[112:115]
	v_mfma_f32_16x16x32_bf16 v[100:103], v[172:175], v[196:199], v[100:103]
	v_mfma_f32_16x16x32_bf16 v[96:99], v[180:183], v[196:199], v[96:99]
	s_barrier
	s_setprio 3
	v_mfma_f32_16x16x32_bf16 v[84:87], v[172:175], v[204:207], v[84:87]
	v_mfma_f32_16x16x32_bf16 v[80:83], v[180:183], v[204:207], v[80:83]
	v_mfma_f32_16x16x32_bf16 v[68:71], v[172:175], v[212:215], v[68:71]
	v_mfma_f32_16x16x32_bf16 v[64:67], v[180:183], v[212:215], v[64:67]
	s_setprio 0
	s_add_i32 s56, s46, s1
	v_lshl_add_u64 v[166:167], s[34:35], 0, v[132:133]
	s_mov_b32 m0, s56
	ds_read_b128 v[184:187], v153 offset:16384
	ds_read_b128 v[188:191], v153 offset:17408
	ds_read_b128 v[192:195], v153 offset:18432
	ds_read_b128 v[196:199], v153 offset:19456
	ds_read_b128 v[200:203], v153 offset:20480
	ds_read_b128 v[204:207], v153 offset:21504
	ds_read_b128 v[208:211], v153 offset:22528
	ds_read_b128 v[212:215], v153 offset:23552
	global_load_lds_dwordx4 v[166:167], off
	s_add_i32 m0, s56, 0x2000
	s_add_u32 s56, s34, 0x80000
	v_lshl_add_u64 v[216:217], s[34:35], 0, v[128:129]
	s_addc_u32 s57, s35, 0
	s_add_i32 s58, s47, s1
	global_load_lds_dwordx4 v[216:217], off
	v_lshl_add_u64 v[218:219], s[56:57], 0, v[132:133]
	s_mov_b32 m0, s58
	v_lshl_add_u64 v[220:221], s[36:37], 0, v[130:131]
	global_load_lds_dwordx4 v[218:219], off
	v_lshl_add_u64 v[218:219], s[56:57], 0, v[128:129]
	s_add_i32 m0, s58, 0x2000
	s_nop 0
	global_load_lds_dwordx4 v[218:219], off
	v_lshl_add_u64 v[218:219], s[36:37], 0, v[134:135]
	s_mov_b32 m0, s29
	s_nop 0
	global_load_lds_dwordx4 v[218:219], off
	s_mov_b32 m0, s38
	s_nop 0
	global_load_lds_dwordx4 v[220:221], off
	s_waitcnt vmcnt(8)
	s_waitcnt lgkmcnt(0)
	s_barrier
; #define PG8_STAGE(bufoff, gbase, voff) do { _Pragma("unroll") for (int _i = 0; _i < 2; ++_i) \
;         __builtin_amdgcn_global_load_lds((const unsigned*)((const char*)(gbase) + (voff)[_i]), (PG8_LAS unsigned*)(lds + (bufoff) + ldsw + _i * 8192), 16, 0, 0); } while (0)
; #define PG8_LDA(dst, b, h) do { _Pragma("unroll") for (int m = 0; m < 4; ++m) _Pragma("unroll") for (int k = 0; k < 2; ++k) dst[m][k] = *(const PG8_LAS bf16x8*)(lds + PG8_SA(b, h) + aoff + m * 2048 + k * 1024); } while (0)
; #define PG8_LDB(dst, b, h) do { _Pragma("unroll") for (int n = 0; n < 2; ++n) _Pragma("unroll") for (int k = 0; k < 2; ++k) dst[n][k] = *(const PG8_LAS bf16x8*)(lds + PG8_SB(b, h) + boff + n * 2048 + k * 1024); } while (0)
; #define PG8_MMA(ai, bj, At, Bt) do { __builtin_amdgcn_s_setprio(1); _Pragma("unroll") for (int m = 0; m < 4; ++m) _Pragma("unroll") for (int n = 0; n < 2; ++n) _Pragma("unroll") for (int k = 0; k < 2; ++k) \
;         acc[ai][bj][m][n] = __builtin_amdgcn_mfma_f32_16x16x32_bf16(Bt[n][k], At[m][k], acc[ai][bj][m][n], 0, 0, 0); __builtin_amdgcn_s_setprio(0); } while (0)
; #define PG8_WAIT_V(n) asm volatile("s_waitcnt vmcnt(" #n ")" ::: "memory")
; #define PG8_WAIT_L(n) asm volatile("s_waitcnt lgkmcnt(" #n ")" ::: "memory")
; #define PG8_BAR __builtin_amdgcn_s_barrier()
; #define PG8_SCHED __builtin_amdgcn_sched_barrier(0)
; template <class Epi, class Sched, bool ALIGN_EPI = false, bool SP2 = false>
; __device__ __forceinline__ void gemm_phase(PG8_LAS unsigned char* lds, const Gemm g, const Sched& S, const Epi& E, int wave_in) {
;     ...
;             PG8_LDA(At, 0, 1); PG8_STAGE(PG8_SB(0, 0), b2, voffB); PG8_STAGE(PG8_SB(0, 1), b2 + hstep, voffB); PG8_STAGE(PG8_SA(0, 0), a2, voffA);
;             PG8_WAIT_V(8); PG8_WAIT_L(0); PG8_BAR; PG8_MMA(1, 0, At, B0); PG8_MMA(1, 1, At, B1); PG8_BAR; PG8_SCHED;
;             PG8_LDB(B0, 1, 0); PG8_LDB(B1, 1, 1); PG8_SCHED; PG8_LDA(At, 1, 0); PG8_STAGE(PG8_SA(0, 1), a2 + hstep, voffA);
;             PG8_WAIT_V(8); PG8_WAIT_L(0); PG8_BAR; PG8_MMA(0, 0, At, B0); PG8_MMA(0, 1, At, B1); PG8_BAR; PG8_SCHED;
	s_setprio 1
	s_waitcnt lgkmcnt(0)
	v_mfma_f32_16x16x32_bf16 v[60:63], v[144:147], v[184:187], v[60:63]
	v_mfma_f32_16x16x32_bf16 v[56:59], v[158:161], v[184:187], v[56:59]
	v_mfma_f32_16x16x32_bf16 v[44:47], v[144:147], v[192:195], v[44:47]
	v_mfma_f32_16x16x32_bf16 v[40:43], v[158:161], v[192:195], v[40:43]
	v_mfma_f32_16x16x32_bf16 v[28:31], v[144:147], v[200:203], v[28:31]
	v_mfma_f32_16x16x32_bf16 v[24:27], v[158:161], v[200:203], v[24:27]
	v_mfma_f32_16x16x32_bf16 v[12:15], v[144:147], v[208:211], v[12:15]
	v_mfma_f32_16x16x32_bf16 v[8:11], v[158:161], v[208:211], v[8:11]
	v_mfma_f32_16x16x32_bf16 v[60:63], v[154:157], v[188:191], v[60:63]
	v_mfma_f32_16x16x32_bf16 v[56:59], v[162:165], v[188:191], v[56:59]
	v_mfma_f32_16x16x32_bf16 v[44:47], v[154:157], v[196:199], v[44:47]
	v_mfma_f32_16x16x32_bf16 v[40:43], v[162:165], v[196:199], v[40:43]
	v_mfma_f32_16x16x32_bf16 v[28:31], v[154:157], v[204:207], v[28:31]
	v_mfma_f32_16x16x32_bf16 v[24:27], v[162:165], v[204:207], v[24:27]
	v_mfma_f32_16x16x32_bf16 v[12:15], v[154:157], v[212:215], v[12:15]
	v_mfma_f32_16x16x32_bf16 v[8:11], v[162:165], v[212:215], v[8:11]
	s_setprio 0
	s_setprio 1
	v_mfma_f32_16x16x32_bf16 v[52:55], v[168:171], v[184:187], v[52:55]
	v_mfma_f32_16x16x32_bf16 v[48:51], v[176:179], v[184:187], v[48:51]
	v_mfma_f32_16x16x32_bf16 v[36:39], v[168:171], v[192:195], v[36:39]
	v_mfma_f32_16x16x32_bf16 v[32:35], v[176:179], v[192:195], v[32:35]
	v_mfma_f32_16x16x32_bf16 v[20:23], v[168:171], v[200:203], v[20:23]
	v_mfma_f32_16x16x32_bf16 v[16:19], v[176:179], v[200:203], v[16:19]
	v_mfma_f32_16x16x32_bf16 v[4:7], v[168:171], v[208:211], v[4:7]
	v_mfma_f32_16x16x32_bf16 v[0:3], v[176:179], v[208:211], v[0:3]
	v_mfma_f32_16x16x32_bf16 v[52:55], v[172:175], v[188:191], v[52:55]
	v_mfma_f32_16x16x32_bf16 v[48:51], v[180:183], v[188:191], v[48:51]
	v_mfma_f32_16x16x32_bf16 v[36:39], v[172:175], v[196:199], v[36:39]
	v_mfma_f32_16x16x32_bf16 v[32:35], v[180:183], v[196:199], v[32:35]
	s_barrier
	s_setprio 3
	v_mfma_f32_16x16x32_bf16 v[20:23], v[172:175], v[204:207], v[20:23]
	v_mfma_f32_16x16x32_bf16 v[16:19], v[180:183], v[204:207], v[16:19]
	v_mfma_f32_16x16x32_bf16 v[4:7], v[172:175], v[212:215], v[4:7]
	v_mfma_f32_16x16x32_bf16 v[0:3], v[180:183], v[212:215], v[0:3]
	s_setprio 0
	s_add_i32 s56, 0, 0x18000
	s_add_i32 s57, 0, 0x1c000
	v_add_u32_e32 v162, s56, v149
	v_add_u32_e32 v180, s57, v149
	ds_read_b128 v[144:147], v162
	ds_read_b128 v[154:157], v162 offset:1024
	ds_read_b128 v[158:161], v162 offset:2048
	ds_read_b128 v[162:165], v162 offset:3072
	ds_read_b128 v[168:171], v180
	ds_read_b128 v[172:175], v180 offset:1024
	ds_read_b128 v[176:179], v180 offset:2048
	ds_read_b128 v[180:183], v180 offset:3072
	s_add_u32 s36, s36, 0x80000
	s_addc_u32 s37, s37, 0
	s_mov_b32 m0, s39
	v_lshl_add_u64 v[222:223], s[36:37], 0, v[134:135]
	ds_read_b128 v[184:187], v153 offset:32768
	ds_read_b128 v[188:191], v153 offset:33792
	ds_read_b128 v[192:195], v153 offset:34816
	ds_read_b128 v[196:199], v153 offset:35840
	ds_read_b128 v[200:203], v153 offset:36864
	ds_read_b128 v[204:207], v153 offset:37888
	ds_read_b128 v[208:211], v153 offset:38912
	ds_read_b128 v[212:215], v153 offset:39936
	global_load_lds_dwordx4 v[222:223], off
	v_lshl_add_u64 v[222:223], s[36:37], 0, v[130:131]
	s_mov_b32 m0, s40
	s_nop 0
	global_load_lds_dwordx4 v[222:223], off
	s_waitcnt vmcnt(8)
	s_waitcnt lgkmcnt(0)
	s_barrier
	s_setprio 1
	s_waitcnt lgkmcnt(0)
	v_mfma_f32_16x16x32_bf16 v[124:127], v[144:147], v[184:187], v[124:127]
	v_mfma_f32_16x16x32_bf16 v[120:123], v[158:161], v[184:187], v[120:123]
	v_mfma_f32_16x16x32_bf16 v[108:111], v[144:147], v[192:195], v[108:111]
	v_mfma_f32_16x16x32_bf16 v[104:107], v[158:161], v[192:195], v[104:107]
	v_mfma_f32_16x16x32_bf16 v[92:95], v[144:147], v[200:203], v[92:95]
	v_mfma_f32_16x16x32_bf16 v[88:91], v[158:161], v[200:203], v[88:91]
	v_mfma_f32_16x16x32_bf16 v[76:79], v[144:147], v[208:211], v[76:79]
	v_mfma_f32_16x16x32_bf16 v[72:75], v[158:161], v[208:211], v[72:75]
	v_mfma_f32_16x16x32_bf16 v[124:127], v[154:157], v[188:191], v[124:127]
	v_mfma_f32_16x16x32_bf16 v[120:123], v[162:165], v[188:191], v[120:123]
	v_mfma_f32_16x16x32_bf16 v[108:111], v[154:157], v[196:199], v[108:111]
	v_mfma_f32_16x16x32_bf16 v[104:107], v[162:165], v[196:199], v[104:107]
	v_mfma_f32_16x16x32_bf16 v[92:95], v[154:157], v[204:207], v[92:95]
	v_mfma_f32_16x16x32_bf16 v[88:91], v[162:165], v[204:207], v[88:91]
	v_mfma_f32_16x16x32_bf16 v[76:79], v[154:157], v[212:215], v[76:79]
	v_mfma_f32_16x16x32_bf16 v[72:75], v[162:165], v[212:215], v[72:75]
	s_setprio 0
	s_setprio 1
	v_mfma_f32_16x16x32_bf16 v[116:119], v[168:171], v[184:187], v[116:119]
	v_mfma_f32_16x16x32_bf16 v[112:115], v[176:179], v[184:187], v[112:115]
	v_mfma_f32_16x16x32_bf16 v[100:103], v[168:171], v[192:195], v[100:103]
	v_mfma_f32_16x16x32_bf16 v[96:99], v[176:179], v[192:195], v[96:99]
	v_mfma_f32_16x16x32_bf16 v[84:87], v[168:171], v[200:203], v[84:87]
	v_mfma_f32_16x16x32_bf16 v[80:83], v[176:179], v[200:203], v[80:83]
	v_mfma_f32_16x16x32_bf16 v[68:71], v[168:171], v[208:211], v[68:71]
	v_mfma_f32_16x16x32_bf16 v[64:67], v[176:179], v[208:211], v[64:67]
	v_mfma_f32_16x16x32_bf16 v[116:119], v[172:175], v[188:191], v[116:119]
	v_mfma_f32_16x16x32_bf16 v[112:115], v[180:183], v[188:191], v[112:115]
	v_mfma_f32_16x16x32_bf16 v[100:103], v[172:175], v[196:199], v[100:103]
	v_mfma_f32_16x16x32_bf16 v[96:99], v[180:183], v[196:199], v[96:99]
	s_barrier
; #define PG8_STAGE(bufoff, gbase, voff) do { _Pragma("unroll") for (int _i = 0; _i < 2; ++_i) \
;         __builtin_amdgcn_global_load_lds((const unsigned*)((const char*)(gbase) + (voff)[_i]), (PG8_LAS unsigned*)(lds + (bufoff) + ldsw + _i * 8192), 16, 0, 0); } while (0)
; #define PG8_LDA(dst, b, h) do { _Pragma("unroll") for (int m = 0; m < 4; ++m) _Pragma("unroll") for (int k = 0; k < 2; ++k) dst[m][k] = *(const PG8_LAS bf16x8*)(lds + PG8_SA(b, h) + aoff + m * 2048 + k * 1024); } while (0)
; #define PG8_LDB(dst, b, h) do { _Pragma("unroll") for (int n = 0; n < 2; ++n) _Pragma("unroll") for (int k = 0; k < 2; ++k) dst[n][k] = *(const PG8_LAS bf16x8*)(lds + PG8_SB(b, h) + boff + n * 2048 + k * 1024); } while (0)
; #define PG8_MMA(ai, bj, At, Bt) do { __builtin_amdgcn_s_setprio(1); _Pragma("unroll") for (int m = 0; m < 4; ++m) _Pragma("unroll") for (int n = 0; n < 2; ++n) _Pragma("unroll") for (int k = 0; k < 2; ++k) \
;         acc[ai][bj][m][n] = __builtin_amdgcn_mfma_f32_16x16x32_bf16(Bt[n][k], At[m][k], acc[ai][bj][m][n], 0, 0, 0); __builtin_amdgcn_s_setprio(0); } while (0)
; #define PG8_WAIT_V(n) asm volatile("s_waitcnt vmcnt(" #n ")" ::: "memory")
; #define PG8_WAIT_L(n) asm volatile("s_waitcnt lgkmcnt(" #n ")" ::: "memory")
; #define PG8_BAR __builtin_amdgcn_s_barrier()
; #define PG8_SCHED __builtin_amdgcn_sched_barrier(0)
; template <class Epi, class Sched, bool ALIGN_EPI = false, bool SP2 = false>
; __device__ __forceinline__ void gemm_phase(PG8_LAS unsigned char* lds, const Gemm g, const Sched& S, const Epi& E, int wave_in) {
;     ...
;             PG8_LDB(B0, 1, 0); PG8_LDB(B1, 1, 1); PG8_SCHED; PG8_LDA(At, 1, 0); PG8_STAGE(PG8_SA(0, 1), a2 + hstep, voffA);
;             PG8_WAIT_V(8); PG8_WAIT_L(0); PG8_BAR; PG8_MMA(0, 0, At, B0); PG8_MMA(0, 1, At, B1); PG8_BAR; PG8_SCHED;
;             PG8_LDA(At, 1, 1); PG8_STAGE(PG8_SB(1, 0), b3, voffB); PG8_STAGE(PG8_SB(1, 1), b3 + hstep, voffB); PG8_STAGE(PG8_SA(1, 0), a3, voffA);
;             PG8_WAIT_V(8); PG8_WAIT_L(0); PG8_BAR; PG8_MMA(1, 0, At, B0); PG8_MMA(1, 1, At, B1); PG8_BAR; PG8_SCHED;
	s_setprio 3
	v_mfma_f32_16x16x32_bf16 v[84:87], v[172:175], v[204:207], v[84:87]
	v_mfma_f32_16x16x32_bf16 v[80:83], v[180:183], v[204:207], v[80:83]
	v_mfma_f32_16x16x32_bf16 v[68:71], v[172:175], v[212:215], v[68:71]
	v_mfma_f32_16x16x32_bf16 v[64:67], v[180:183], v[212:215], v[64:67]
	s_setprio 0
	s_add_i32 s36, s56, s1
	v_lshl_add_u64 v[166:167], v[166:167], 0, s[10:11]
	s_mov_b32 m0, s36
	ds_read_b128 v[184:187], v153 offset:49152
	ds_read_b128 v[188:191], v153 offset:50176
	ds_read_b128 v[192:195], v153 offset:51200
	ds_read_b128 v[196:199], v153 offset:52224
	ds_read_b128 v[200:203], v153 offset:53248
	ds_read_b128 v[204:207], v153 offset:54272
	ds_read_b128 v[208:211], v153 offset:55296
	ds_read_b128 v[212:215], v153 offset:56320
	global_load_lds_dwordx4 v[166:167], off
	s_add_i32 m0, s36, 0x2000
	s_add_u32 s34, s34, 0x80080
	v_lshl_add_u64 v[166:167], v[216:217], 0, s[10:11]
	s_addc_u32 s35, s35, 0
	s_add_i32 s36, s57, s1
	global_load_lds_dwordx4 v[166:167], off
	v_lshl_add_u64 v[166:167], s[34:35], 0, v[132:133]
	s_mov_b32 m0, s36
	s_nop 0
	global_load_lds_dwordx4 v[166:167], off
	v_lshl_add_u64 v[166:167], s[34:35], 0, v[128:129]
	s_add_i32 m0, s36, 0x2000
	s_nop 0
	global_load_lds_dwordx4 v[166:167], off
	v_lshl_add_u64 v[166:167], v[218:219], 0, s[10:11]
	s_mov_b32 m0, s42
	s_nop 0
	global_load_lds_dwordx4 v[166:167], off
	v_lshl_add_u64 v[166:167], v[220:221], 0, s[10:11]
	s_mov_b32 m0, s43
	s_nop 0
	global_load_lds_dwordx4 v[166:167], off
	s_waitcnt vmcnt(8)
	s_waitcnt lgkmcnt(0)
	s_barrier
	s_setprio 1
	s_waitcnt lgkmcnt(0)
	v_mfma_f32_16x16x32_bf16 v[60:63], v[144:147], v[184:187], v[60:63]
	v_mfma_f32_16x16x32_bf16 v[56:59], v[158:161], v[184:187], v[56:59]
	v_mfma_f32_16x16x32_bf16 v[44:47], v[144:147], v[192:195], v[44:47]
	v_mfma_f32_16x16x32_bf16 v[40:43], v[158:161], v[192:195], v[40:43]
	v_mfma_f32_16x16x32_bf16 v[28:31], v[144:147], v[200:203], v[28:31]
	v_mfma_f32_16x16x32_bf16 v[24:27], v[158:161], v[200:203], v[24:27]
	v_mfma_f32_16x16x32_bf16 v[12:15], v[144:147], v[208:211], v[12:15]
	v_mfma_f32_16x16x32_bf16 v[8:11], v[158:161], v[208:211], v[8:11]
	v_mfma_f32_16x16x32_bf16 v[60:63], v[154:157], v[188:191], v[60:63]
	v_mfma_f32_16x16x32_bf16 v[56:59], v[162:165], v[188:191], v[56:59]
	v_mfma_f32_16x16x32_bf16 v[44:47], v[154:157], v[196:199], v[44:47]
	v_mfma_f32_16x16x32_bf16 v[40:43], v[162:165], v[196:199], v[40:43]
	v_mfma_f32_16x16x32_bf16 v[28:31], v[154:157], v[204:207], v[28:31]
	v_mfma_f32_16x16x32_bf16 v[24:27], v[162:165], v[204:207], v[24:27]
	v_mfma_f32_16x16x32_bf16 v[12:15], v[154:157], v[212:215], v[12:15]
	v_mfma_f32_16x16x32_bf16 v[8:11], v[162:165], v[212:215], v[8:11]
	s_setprio 0
	s_setprio 1
	v_mfma_f32_16x16x32_bf16 v[52:55], v[168:171], v[184:187], v[52:55]
	v_mfma_f32_16x16x32_bf16 v[48:51], v[176:179], v[184:187], v[48:51]
	v_mfma_f32_16x16x32_bf16 v[36:39], v[168:171], v[192:195], v[36:39]
	v_mfma_f32_16x16x32_bf16 v[32:35], v[176:179], v[192:195], v[32:35]
	v_mfma_f32_16x16x32_bf16 v[20:23], v[168:171], v[200:203], v[20:23]
	v_mfma_f32_16x16x32_bf16 v[16:19], v[176:179], v[200:203], v[16:19]
	v_mfma_f32_16x16x32_bf16 v[4:7], v[168:171], v[208:211], v[4:7]
	v_mfma_f32_16x16x32_bf16 v[0:3], v[176:179], v[208:211], v[0:3]
	v_mfma_f32_16x16x32_bf16 v[52:55], v[172:175], v[188:191], v[52:55]
	v_mfma_f32_16x16x32_bf16 v[48:51], v[180:183], v[188:191], v[48:51]
	v_mfma_f32_16x16x32_bf16 v[36:39], v[172:175], v[196:199], v[36:39]
	v_mfma_f32_16x16x32_bf16 v[32:35], v[180:183], v[196:199], v[32:35]
	s_barrier
	s_setprio 3
	v_mfma_f32_16x16x32_bf16 v[20:23], v[172:175], v[204:207], v[20:23]
	v_mfma_f32_16x16x32_bf16 v[16:19], v[180:183], v[204:207], v[16:19]
	v_mfma_f32_16x16x32_bf16 v[4:7], v[172:175], v[212:215], v[4:7]
	v_mfma_f32_16x16x32_bf16 v[0:3], v[180:183], v[212:215], v[0:3]
	s_setprio 0
	s_add_i32 s55, s55, 2
	s_add_u32 s30, s30, 0x100
	s_addc_u32 s31, s31, 0
	s_add_u32 s52, s52, 0x100
	s_addc_u32 s53, s53, 0
	s_cmp_gt_u32 s55, 29
	s_cbranch_scc0 .LBB0_184
	s_and_b64 vcc, exec, s[16:17]
	s_cbranch_vccz .LBB0_187
	s_barrier

; #define PG8_STAGE(bufoff, gbase, voff) do { _Pragma("unroll") for (int _i = 0; _i < 2; ++_i) \
;         __builtin_amdgcn_global_load_lds((const unsigned*)((const char*)(gbase) + (voff)[_i]), (PG8_LAS unsigned*)(lds + (bufoff) + ldsw + _i * 8192), 16, 0, 0); } while (0)
; #define PG8_LDA(dst, b, h) do { _Pragma("unroll") for (int m = 0; m < 4; ++m) _Pragma("unroll") for (int k = 0; k < 2; ++k) dst[m][k] = *(const PG8_LAS bf16x8*)(lds + PG8_SA(b, h) + aoff + m * 2048 + k * 1024); } while (0)
; #define PG8_LDB(dst, b, h) do { _Pragma("unroll") for (int n = 0; n < 2; ++n) _Pragma("unroll") for (int k = 0; k < 2; ++k) dst[n][k] = *(const PG8_LAS bf16x8*)(lds + PG8_SB(b, h) + boff + n * 2048 + k * 1024); } while (0)
; #define PG8_MMA(ai, bj, At, Bt) do { __builtin_amdgcn_s_setprio(1); _Pragma("unroll") for (int m = 0; m < 4; ++m) _Pragma("unroll") for (int n = 0; n < 2; ++n) _Pragma("unroll") for (int k = 0; k < 2; ++k) \
;         acc[ai][bj][m][n] = __builtin_amdgcn_mfma_f32_16x16x32_bf16(Bt[n][k], At[m][k], acc[ai][bj][m][n], 0, 0, 0); __builtin_amdgcn_s_setprio(0); } while (0)
; #define PG8_WAIT_V(n) asm volatile("s_waitcnt vmcnt(" #n ")" ::: "memory")
; #define PG8_WAIT_L(n) asm volatile("s_waitcnt lgkmcnt(" #n ")" ::: "memory")
; #define PG8_BAR __builtin_amdgcn_s_barrier()
; #define PG8_SCHED __builtin_amdgcn_sched_barrier(0)
; template <class Epi, class Sched, bool ALIGN_EPI = false, bool SP2 = false>
; __device__ __forceinline__ void gemm_phase(PG8_LAS unsigned char* lds, const Gemm g, const Sched& S, const Epi& E, int wave_in) {
;     ...
;             const bool last = (t == nt - 2);
;             const char* a1 = cA + (size_t)(t + 1) * kstep;
;             const char* a2 = last ? nA : cA + (size_t)(t + 2) * kstep; const char* b2 = last ? nB : cB + (size_t)(t + 2) * kstep;
;             const char* a3 = a2 + kstep; const char* b3 = b2 + kstep;
;             if (last && has_next) S.a_ready(nxt);
;             if constexpr (SP2) {
;             PG8_LDB(B0, 0, 0); PG8_LDB(B1, 0, 1); PG8_SCHED; PG8_LDA(At, 0, 0); PG8_STAGE(PG8_SA(1, 1), a1 + hstep, voffA);
;             PG8_WAIT_V(8); PG8_WAIT_L(0); PG8_BAR; PG8_MMA(0, 0, At, B0); PG8_MMA(0, 1, At, B1); PG8_BAR; PG8_SCHED;
;             PG8_LDA(At, 0, 1); PG8_STAGE(PG8_SB(0, 0), b2, voffB); PG8_STAGE(PG8_SB(0, 1), b2 + hstep, voffB); PG8_STAGE(PG8_SA(0, 0), a2, voffA);
.LBB0_307:
	ds_read_b128 v[140:143], v147
	ds_read_b128 v[152:155], v147 offset:1024
	ds_read_b128 v[156:159], v147 offset:2048
	ds_read_b128 v[160:163], v147 offset:3072
	ds_read_b128 v[168:171], v148
	ds_read_b128 v[172:175], v148 offset:1024
	ds_read_b128 v[176:179], v148 offset:2048
	ds_read_b128 v[180:183], v148 offset:3072
	s_add_u32 s28, s26, 0x100
	s_addc_u32 s29, s27, 0
	s_cmpk_eq_i32 s55, 0x54
	s_cselect_b32 s35, s5, s29
	s_cselect_b32 s34, s4, s28
	s_cselect_b32 s31, s25, s54
	s_cselect_b32 s30, s24, s53
	v_lshl_add_u64 v[164:165], s[26:27], 0, v[132:133]
	s_add_i32 m0, s37, 0xc000
	ds_read_b128 v[184:187], v149
	ds_read_b128 v[188:191], v149 offset:1024
	ds_read_b128 v[192:195], v149 offset:2048
	ds_read_b128 v[196:199], v149 offset:3072
	ds_read_b128 v[200:203], v149 offset:4096
	ds_read_b128 v[204:207], v149 offset:5120
	ds_read_b128 v[208:211], v149 offset:6144
	ds_read_b128 v[212:215], v149 offset:7168
	global_load_lds_dwordx4 v[164:165], off
	v_lshl_add_u64 v[164:165], s[26:27], 0, v[134:135]
	s_add_i32 m0, s37, 0xe000
	s_nop 0
	global_load_lds_dwordx4 v[164:165], off
	s_waitcnt vmcnt(8)
	s_waitcnt lgkmcnt(0)
	s_barrier
	s_setprio 1
	s_waitcnt lgkmcnt(0)
	v_mfma_f32_16x16x32_bf16 v[124:127], v[140:143], v[184:187], v[124:127]
	v_mfma_f32_16x16x32_bf16 v[120:123], v[156:159], v[184:187], v[120:123]
	v_mfma_f32_16x16x32_bf16 v[108:111], v[140:143], v[192:195], v[108:111]
	v_mfma_f32_16x16x32_bf16 v[104:107], v[156:159], v[192:195], v[104:107]
	v_mfma_f32_16x16x32_bf16 v[92:95], v[140:143], v[200:203], v[92:95]
	v_mfma_f32_16x16x32_bf16 v[88:91], v[156:159], v[200:203], v[88:91]
	v_mfma_f32_16x16x32_bf16 v[76:79], v[140:143], v[208:211], v[76:79]
	v_mfma_f32_16x16x32_bf16 v[72:75], v[156:159], v[208:211], v[72:75]
	v_mfma_f32_16x16x32_bf16 v[124:127], v[152:155], v[188:191], v[124:127]
	v_mfma_f32_16x16x32_bf16 v[120:123], v[160:163], v[188:191], v[120:123]
	v_mfma_f32_16x16x32_bf16 v[108:111], v[152:155], v[196:199], v[108:111]
	v_mfma_f32_16x16x32_bf16 v[104:107], v[160:163], v[196:199], v[104:107]
	v_mfma_f32_16x16x32_bf16 v[92:95], v[152:155], v[204:207], v[92:95]
	v_mfma_f32_16x16x32_bf16 v[88:91], v[160:163], v[204:207], v[88:91]
	v_mfma_f32_16x16x32_bf16 v[76:79], v[152:155], v[212:215], v[76:79]
	v_mfma_f32_16x16x32_bf16 v[72:75], v[160:163], v[212:215], v[72:75]
	s_setprio 0
	s_setprio 1
	v_mfma_f32_16x16x32_bf16 v[116:119], v[168:171], v[184:187], v[116:119]
	v_mfma_f32_16x16x32_bf16 v[112:115], v[176:179], v[184:187], v[112:115]
	v_mfma_f32_16x16x32_bf16 v[100:103], v[168:171], v[192:195], v[100:103]
	v_mfma_f32_16x16x32_bf16 v[96:99], v[176:179], v[192:195], v[96:99]
	v_mfma_f32_16x16x32_bf16 v[84:87], v[168:171], v[200:203], v[84:87]
	v_mfma_f32_16x16x32_bf16 v[80:83], v[176:179], v[200:203], v[80:83]
	v_mfma_f32_16x16x32_bf16 v[68:71], v[168:171], v[208:211], v[68:71]
	v_mfma_f32_16x16x32_bf16 v[64:67], v[176:179], v[208:211], v[64:67]
	v_mfma_f32_16x16x32_bf16 v[116:119], v[172:175], v[188:191], v[116:119]
	v_mfma_f32_16x16x32_bf16 v[112:115], v[180:183], v[188:191], v[112:115]
	v_mfma_f32_16x16x32_bf16 v[100:103], v[172:175], v[196:199], v[100:103]
	v_mfma_f32_16x16x32_bf16 v[96:99], v[180:183], v[196:199], v[96:99]
	s_barrier
	s_setprio 3
	v_mfma_f32_16x16x32_bf16 v[84:87], v[172:175], v[204:207], v[84:87]
	v_mfma_f32_16x16x32_bf16 v[80:83], v[180:183], v[204:207], v[80:83]
	v_mfma_f32_16x16x32_bf16 v[68:71], v[172:175], v[212:215], v[68:71]
	v_mfma_f32_16x16x32_bf16 v[64:67], v[180:183], v[212:215], v[64:67]
	s_setprio 0
	s_add_i32 s26, s47, s21
	v_lshl_add_u64 v[164:165], s[30:31], 0, v[128:129]
	s_mov_b32 m0, s26
	ds_read_b128 v[184:187], v149 offset:16384
	ds_read_b128 v[188:191], v149 offset:17408
	ds_read_b128 v[192:195], v149 offset:18432
	ds_read_b128 v[196:199], v149 offset:19456
	ds_read_b128 v[200:203], v149 offset:20480
	ds_read_b128 v[204:207], v149 offset:21504
	ds_read_b128 v[208:211], v149 offset:22528
	ds_read_b128 v[212:215], v149 offset:23552
	global_load_lds_dwordx4 v[164:165], off
	s_add_i32 m0, s26, 0x2000
	s_add_u32 s26, s30, 0x160000
	v_lshl_add_u64 v[166:167], s[30:31], 0, v[130:131]
	s_addc_u32 s27, s31, 0
	s_add_i32 s56, s48, s21
	global_load_lds_dwordx4 v[166:167], off
	v_lshl_add_u64 v[216:217], s[26:27], 0, v[128:129]
	s_mov_b32 m0, s56
	v_lshl_add_u64 v[218:219], s[34:35], 0, v[130:131]
	global_load_lds_dwordx4 v[216:217], off
	v_lshl_add_u64 v[216:217], s[26:27], 0, v[130:131]
	s_add_i32 m0, s56, 0x2000
	s_nop 0
	global_load_lds_dwordx4 v[216:217], off
	v_lshl_add_u64 v[216:217], s[34:35], 0, v[128:129]
	s_mov_b32 m0, s37
	s_nop 0
	global_load_lds_dwordx4 v[216:217], off
	s_mov_b32 m0, s38
	s_nop 0
	global_load_lds_dwordx4 v[218:219], off
	s_waitcnt vmcnt(8)
	s_waitcnt lgkmcnt(0)
	s_barrier
; #define PG8_STAGE(bufoff, gbase, voff) do { _Pragma("unroll") for (int _i = 0; _i < 2; ++_i) \
;         __builtin_amdgcn_global_load_lds((const unsigned*)((const char*)(gbase) + (voff)[_i]), (PG8_LAS unsigned*)(lds + (bufoff) + ldsw + _i * 8192), 16, 0, 0); } while (0)
; #define PG8_LDA(dst, b, h) do { _Pragma("unroll") for (int m = 0; m < 4; ++m) _Pragma("unroll") for (int k = 0; k < 2; ++k) dst[m][k] = *(const PG8_LAS bf16x8*)(lds + PG8_SA(b, h) + aoff + m * 2048 + k * 1024); } while (0)
; #define PG8_LDB(dst, b, h) do { _Pragma("unroll") for (int n = 0; n < 2; ++n) _Pragma("unroll") for (int k = 0; k < 2; ++k) dst[n][k] = *(const PG8_LAS bf16x8*)(lds + PG8_SB(b, h) + boff + n * 2048 + k * 1024); } while (0)
; #define PG8_MMA(ai, bj, At, Bt) do { __builtin_amdgcn_s_setprio(1); _Pragma("unroll") for (int m = 0; m < 4; ++m) _Pragma("unroll") for (int n = 0; n < 2; ++n) _Pragma("unroll") for (int k = 0; k < 2; ++k) \
;         acc[ai][bj][m][n] = __builtin_amdgcn_mfma_f32_16x16x32_bf16(Bt[n][k], At[m][k], acc[ai][bj][m][n], 0, 0, 0); __builtin_amdgcn_s_setprio(0); } while (0)
; #define PG8_WAIT_V(n) asm volatile("s_waitcnt vmcnt(" #n ")" ::: "memory")
; #define PG8_WAIT_L(n) asm volatile("s_waitcnt lgkmcnt(" #n ")" ::: "memory")
; #define PG8_BAR __builtin_amdgcn_s_barrier()
; #define PG8_SCHED __builtin_amdgcn_sched_barrier(0)
; template <class Epi, class Sched, bool ALIGN_EPI = false, bool SP2 = false>
; __device__ __forceinline__ void gemm_phase(PG8_LAS unsigned char* lds, const Gemm g, const Sched& S, const Epi& E, int wave_in) {
;     ...
;             PG8_LDA(At, 0, 1); PG8_STAGE(PG8_SB(0, 0), b2, voffB); PG8_STAGE(PG8_SB(0, 1), b2 + hstep, voffB); PG8_STAGE(PG8_SA(0, 0), a2, voffA);
;             PG8_WAIT_V(8); PG8_WAIT_L(0); PG8_BAR; PG8_MMA(1, 0, At, B0); PG8_MMA(1, 1, At, B1); PG8_BAR; PG8_SCHED;
;             PG8_LDB(B0, 1, 0); PG8_LDB(B1, 1, 1); PG8_SCHED; PG8_LDA(At, 1, 0); PG8_STAGE(PG8_SA(0, 1), a2 + hstep, voffA);
;             PG8_WAIT_V(8); PG8_WAIT_L(0); PG8_BAR; PG8_MMA(0, 0, At, B0); PG8_MMA(0, 1, At, B1); PG8_BAR; PG8_SCHED;
	s_setprio 1
	s_waitcnt lgkmcnt(0)
	v_mfma_f32_16x16x32_bf16 v[60:63], v[140:143], v[184:187], v[60:63]
	v_mfma_f32_16x16x32_bf16 v[56:59], v[156:159], v[184:187], v[56:59]
	v_mfma_f32_16x16x32_bf16 v[44:47], v[140:143], v[192:195], v[44:47]
	v_mfma_f32_16x16x32_bf16 v[40:43], v[156:159], v[192:195], v[40:43]
	v_mfma_f32_16x16x32_bf16 v[28:31], v[140:143], v[200:203], v[28:31]
	v_mfma_f32_16x16x32_bf16 v[24:27], v[156:159], v[200:203], v[24:27]
	v_mfma_f32_16x16x32_bf16 v[12:15], v[140:143], v[208:211], v[12:15]
	v_mfma_f32_16x16x32_bf16 v[8:11], v[156:159], v[208:211], v[8:11]
	v_mfma_f32_16x16x32_bf16 v[60:63], v[152:155], v[188:191], v[60:63]
	v_mfma_f32_16x16x32_bf16 v[56:59], v[160:163], v[188:191], v[56:59]
	v_mfma_f32_16x16x32_bf16 v[44:47], v[152:155], v[196:199], v[44:47]
	v_mfma_f32_16x16x32_bf16 v[40:43], v[160:163], v[196:199], v[40:43]
	v_mfma_f32_16x16x32_bf16 v[28:31], v[152:155], v[204:207], v[28:31]
	v_mfma_f32_16x16x32_bf16 v[24:27], v[160:163], v[204:207], v[24:27]
	v_mfma_f32_16x16x32_bf16 v[12:15], v[152:155], v[212:215], v[12:15]
	v_mfma_f32_16x16x32_bf16 v[8:11], v[160:163], v[212:215], v[8:11]
	s_setprio 0
	s_setprio 1
	v_mfma_f32_16x16x32_bf16 v[52:55], v[168:171], v[184:187], v[52:55]
	v_mfma_f32_16x16x32_bf16 v[48:51], v[176:179], v[184:187], v[48:51]
	v_mfma_f32_16x16x32_bf16 v[36:39], v[168:171], v[192:195], v[36:39]
	v_mfma_f32_16x16x32_bf16 v[32:35], v[176:179], v[192:195], v[32:35]
	v_mfma_f32_16x16x32_bf16 v[20:23], v[168:171], v[200:203], v[20:23]
	v_mfma_f32_16x16x32_bf16 v[16:19], v[176:179], v[200:203], v[16:19]
	v_mfma_f32_16x16x32_bf16 v[4:7], v[168:171], v[208:211], v[4:7]
	v_mfma_f32_16x16x32_bf16 v[0:3], v[176:179], v[208:211], v[0:3]
	v_mfma_f32_16x16x32_bf16 v[52:55], v[172:175], v[188:191], v[52:55]
	v_mfma_f32_16x16x32_bf16 v[48:51], v[180:183], v[188:191], v[48:51]
	v_mfma_f32_16x16x32_bf16 v[36:39], v[172:175], v[196:199], v[36:39]
	v_mfma_f32_16x16x32_bf16 v[32:35], v[180:183], v[196:199], v[32:35]
	s_barrier
	s_setprio 3
	v_mfma_f32_16x16x32_bf16 v[20:23], v[172:175], v[204:207], v[20:23]
	v_mfma_f32_16x16x32_bf16 v[16:19], v[180:183], v[204:207], v[16:19]
	v_mfma_f32_16x16x32_bf16 v[4:7], v[172:175], v[212:215], v[4:7]
	v_mfma_f32_16x16x32_bf16 v[0:3], v[180:183], v[212:215], v[0:3]
	s_setprio 0
	s_add_i32 s56, 0, 0x18000
	v_add_u32_e32 v151, s56, v145
	s_add_i32 s57, 0, 0x1c000
	ds_read_b128 v[140:143], v151
	ds_read_b128 v[152:155], v151 offset:1024
	ds_read_b128 v[156:159], v151 offset:2048
	ds_read_b128 v[160:163], v151 offset:3072
	v_add_u32_e32 v151, s57, v145
	ds_read_b128 v[168:171], v151
	ds_read_b128 v[172:175], v151 offset:1024
	ds_read_b128 v[176:179], v151 offset:2048
	ds_read_b128 v[180:183], v151 offset:3072
	s_add_u32 s26, s34, 0x160000
	s_addc_u32 s27, s35, 0
	s_mov_b32 m0, s39
	v_lshl_add_u64 v[220:221], s[26:27], 0, v[128:129]
	ds_read_b128 v[184:187], v149 offset:32768
	ds_read_b128 v[188:191], v149 offset:33792
	ds_read_b128 v[192:195], v149 offset:34816
	ds_read_b128 v[196:199], v149 offset:35840
	ds_read_b128 v[200:203], v149 offset:36864
	ds_read_b128 v[204:207], v149 offset:37888
	ds_read_b128 v[208:211], v149 offset:38912
	ds_read_b128 v[212:215], v149 offset:39936
	global_load_lds_dwordx4 v[220:221], off
	v_lshl_add_u64 v[220:221], s[26:27], 0, v[130:131]
	s_mov_b32 m0, s40
	s_nop 0
	global_load_lds_dwordx4 v[220:221], off
	s_waitcnt vmcnt(8)
	s_waitcnt lgkmcnt(0)
	s_barrier
	s_setprio 1
	s_waitcnt lgkmcnt(0)
	v_mfma_f32_16x16x32_bf16 v[124:127], v[140:143], v[184:187], v[124:127]
	v_mfma_f32_16x16x32_bf16 v[120:123], v[156:159], v[184:187], v[120:123]
	v_mfma_f32_16x16x32_bf16 v[108:111], v[140:143], v[192:195], v[108:111]
	v_mfma_f32_16x16x32_bf16 v[104:107], v[156:159], v[192:195], v[104:107]
	v_mfma_f32_16x16x32_bf16 v[92:95], v[140:143], v[200:203], v[92:95]
	v_mfma_f32_16x16x32_bf16 v[88:91], v[156:159], v[200:203], v[88:91]
	v_mfma_f32_16x16x32_bf16 v[76:79], v[140:143], v[208:211], v[76:79]
	v_mfma_f32_16x16x32_bf16 v[72:75], v[156:159], v[208:211], v[72:75]
	v_mfma_f32_16x16x32_bf16 v[124:127], v[152:155], v[188:191], v[124:127]
	v_mfma_f32_16x16x32_bf16 v[120:123], v[160:163], v[188:191], v[120:123]
	v_mfma_f32_16x16x32_bf16 v[108:111], v[152:155], v[196:199], v[108:111]
	v_mfma_f32_16x16x32_bf16 v[104:107], v[160:163], v[196:199], v[104:107]
	v_mfma_f32_16x16x32_bf16 v[92:95], v[152:155], v[204:207], v[92:95]
	v_mfma_f32_16x16x32_bf16 v[88:91], v[160:163], v[204:207], v[88:91]
	v_mfma_f32_16x16x32_bf16 v[76:79], v[152:155], v[212:215], v[76:79]
	v_mfma_f32_16x16x32_bf16 v[72:75], v[160:163], v[212:215], v[72:75]
	s_setprio 0
	s_setprio 1
	v_mfma_f32_16x16x32_bf16 v[116:119], v[168:171], v[184:187], v[116:119]
	v_mfma_f32_16x16x32_bf16 v[112:115], v[176:179], v[184:187], v[112:115]
	v_mfma_f32_16x16x32_bf16 v[100:103], v[168:171], v[192:195], v[100:103]
	v_mfma_f32_16x16x32_bf16 v[96:99], v[176:179], v[192:195], v[96:99]
	v_mfma_f32_16x16x32_bf16 v[84:87], v[168:171], v[200:203], v[84:87]
	v_mfma_f32_16x16x32_bf16 v[80:83], v[176:179], v[200:203], v[80:83]
	v_mfma_f32_16x16x32_bf16 v[68:71], v[168:171], v[208:211], v[68:71]
	v_mfma_f32_16x16x32_bf16 v[64:67], v[176:179], v[208:211], v[64:67]
	v_mfma_f32_16x16x32_bf16 v[116:119], v[172:175], v[188:191], v[116:119]
	v_mfma_f32_16x16x32_bf16 v[112:115], v[180:183], v[188:191], v[112:115]
	v_mfma_f32_16x16x32_bf16 v[100:103], v[172:175], v[196:199], v[100:103]
	v_mfma_f32_16x16x32_bf16 v[96:99], v[180:183], v[196:199], v[96:99]
	s_barrier
; #define PG8_STAGE(bufoff, gbase, voff) do { _Pragma("unroll") for (int _i = 0; _i < 2; ++_i) \
;         __builtin_amdgcn_global_load_lds((const unsigned*)((const char*)(gbase) + (voff)[_i]), (PG8_LAS unsigned*)(lds + (bufoff) + ldsw + _i * 8192), 16, 0, 0); } while (0)
; #define PG8_LDA(dst, b, h) do { _Pragma("unroll") for (int m = 0; m < 4; ++m) _Pragma("unroll") for (int k = 0; k < 2; ++k) dst[m][k] = *(const PG8_LAS bf16x8*)(lds + PG8_SA(b, h) + aoff + m * 2048 + k * 1024); } while (0)
; #define PG8_MMA(ai, bj, At, Bt) do { __builtin_amdgcn_s_setprio(1); _Pragma("unroll") for (int m = 0; m < 4; ++m) _Pragma("unroll") for (int n = 0; n < 2; ++n) _Pragma("unroll") for (int k = 0; k < 2; ++k) \
;         acc[ai][bj][m][n] = __builtin_amdgcn_mfma_f32_16x16x32_bf16(Bt[n][k], At[m][k], acc[ai][bj][m][n], 0, 0, 0); __builtin_amdgcn_s_setprio(0); } while (0)
;     __device__ __forceinline__ void operator()(const f32x4 (&acc)[2][2][4][2], const Unit& u, int wr, int wc, int fr, int fq) const {
;     ...
;             for (int m = 0; m < 4; ++m) { const int row = u.pm * BM + ai * HALF + wr * 64 + m * 16 + fr; const size_t off = (size_t)row * ldc + col0;
;                 float ss = 0.f;
; #pragma unroll
;                 for (int bj = 0; bj < 2; ++bj)
; #pragma unroll
;                     for (int n = 0; n < 2; ++n) { f32x4 bs;
;                         if (BASE_BF16) { const u32x2 t = *(const u32x2*)((const bf16_t*)base + off + bj * HALF + n * 16);
;                             bs = (f32x4){__builtin_bit_cast(float, t.x << 16), __builtin_bit_cast(float, t.x & 0xffff0000u), __builtin_bit_cast(float, t.y << 16), __builtin_bit_cast(float, t.y & 0xffff0000u)}; }
;                         else bs = *(const f32x4*)((const float*)base + off + bj * HALF + n * 16);
; template <class Epi, class Sched, bool ALIGN_EPI = false, bool SP2 = false>
; __device__ __forceinline__ void gemm_phase(PG8_LAS unsigned char* lds, const Gemm g, const Sched& S, const Epi& E, int wave_in) {
;     ...
;             PG8_WAIT_V(8); PG8_WAIT_L(0); PG8_BAR; PG8_MMA(0, 0, At, B0); PG8_MMA(0, 1, At, B1); PG8_BAR; PG8_SCHED;
;             PG8_LDA(At, 1, 1); PG8_STAGE(PG8_SB(1, 0), b3, voffB); PG8_STAGE(PG8_SB(1, 1), b3 + hstep, voffB); PG8_STAGE(PG8_SA(1, 0), a3, voffA);
;             PG8_WAIT_V(8); PG8_WAIT_L(0); PG8_BAR; PG8_MMA(1, 0, At, B0); PG8_MMA(1, 1, At, B1); PG8_BAR; PG8_SCHED;
	s_setprio 3
	v_mfma_f32_16x16x32_bf16 v[84:87], v[172:175], v[204:207], v[84:87]
	v_mfma_f32_16x16x32_bf16 v[80:83], v[180:183], v[204:207], v[80:83]
	v_mfma_f32_16x16x32_bf16 v[68:71], v[172:175], v[212:215], v[68:71]
	v_mfma_f32_16x16x32_bf16 v[64:67], v[180:183], v[212:215], v[64:67]
	s_setprio 0
	s_add_i32 s26, s56, s21
	v_lshl_add_u64 v[164:165], v[164:165], 0, s[10:11]
	s_mov_b32 m0, s26
	ds_read_b128 v[184:187], v149 offset:49152
	ds_read_b128 v[188:191], v149 offset:50176
	ds_read_b128 v[192:195], v149 offset:51200
	ds_read_b128 v[196:199], v149 offset:52224
	ds_read_b128 v[200:203], v149 offset:53248
	ds_read_b128 v[204:207], v149 offset:54272
	ds_read_b128 v[208:211], v149 offset:55296
	ds_read_b128 v[212:215], v149 offset:56320
	global_load_lds_dwordx4 v[164:165], off
	s_add_i32 m0, s26, 0x2000
	s_add_u32 s26, s30, 0x160080
	v_lshl_add_u64 v[164:165], v[166:167], 0, s[10:11]
	s_addc_u32 s27, s31, 0
	s_add_i32 s30, s57, s21
	global_load_lds_dwordx4 v[164:165], off
	v_lshl_add_u64 v[164:165], s[26:27], 0, v[128:129]
	s_mov_b32 m0, s30
	s_nop 0
	global_load_lds_dwordx4 v[164:165], off
	v_lshl_add_u64 v[164:165], s[26:27], 0, v[130:131]
	s_add_i32 m0, s30, 0x2000
	s_nop 0
	global_load_lds_dwordx4 v[164:165], off
	v_lshl_add_u64 v[164:165], v[216:217], 0, s[10:11]
	s_mov_b32 m0, s42
	s_nop 0
	global_load_lds_dwordx4 v[164:165], off
	v_lshl_add_u64 v[164:165], v[218:219], 0, s[10:11]
	s_mov_b32 m0, s43
	s_nop 0
	global_load_lds_dwordx4 v[164:165], off
	s_waitcnt vmcnt(8)
	s_waitcnt lgkmcnt(0)
	s_barrier
	s_setprio 1
	s_waitcnt lgkmcnt(0)
	v_mfma_f32_16x16x32_bf16 v[60:63], v[140:143], v[184:187], v[60:63]
	v_mfma_f32_16x16x32_bf16 v[56:59], v[156:159], v[184:187], v[56:59]
	v_mfma_f32_16x16x32_bf16 v[44:47], v[140:143], v[192:195], v[44:47]
	v_mfma_f32_16x16x32_bf16 v[40:43], v[156:159], v[192:195], v[40:43]
	v_mfma_f32_16x16x32_bf16 v[28:31], v[140:143], v[200:203], v[28:31]
	v_mfma_f32_16x16x32_bf16 v[24:27], v[156:159], v[200:203], v[24:27]
	v_mfma_f32_16x16x32_bf16 v[12:15], v[140:143], v[208:211], v[12:15]
	v_mfma_f32_16x16x32_bf16 v[8:11], v[156:159], v[208:211], v[8:11]
	v_mfma_f32_16x16x32_bf16 v[60:63], v[152:155], v[188:191], v[60:63]
	v_mfma_f32_16x16x32_bf16 v[56:59], v[160:163], v[188:191], v[56:59]
	v_mfma_f32_16x16x32_bf16 v[44:47], v[152:155], v[196:199], v[44:47]
	v_mfma_f32_16x16x32_bf16 v[40:43], v[160:163], v[196:199], v[40:43]
	v_mfma_f32_16x16x32_bf16 v[28:31], v[152:155], v[204:207], v[28:31]
	v_mfma_f32_16x16x32_bf16 v[24:27], v[160:163], v[204:207], v[24:27]
	v_mfma_f32_16x16x32_bf16 v[12:15], v[152:155], v[212:215], v[12:15]
	v_mfma_f32_16x16x32_bf16 v[8:11], v[160:163], v[212:215], v[8:11]
	s_setprio 0
	s_setprio 1
	v_mfma_f32_16x16x32_bf16 v[52:55], v[168:171], v[184:187], v[52:55]
	v_mfma_f32_16x16x32_bf16 v[48:51], v[176:179], v[184:187], v[48:51]
	v_mfma_f32_16x16x32_bf16 v[36:39], v[168:171], v[192:195], v[36:39]
	v_mfma_f32_16x16x32_bf16 v[32:35], v[176:179], v[192:195], v[32:35]
	v_mfma_f32_16x16x32_bf16 v[20:23], v[168:171], v[200:203], v[20:23]
	v_mfma_f32_16x16x32_bf16 v[16:19], v[176:179], v[200:203], v[16:19]
	v_mfma_f32_16x16x32_bf16 v[4:7], v[168:171], v[208:211], v[4:7]
	v_mfma_f32_16x16x32_bf16 v[0:3], v[176:179], v[208:211], v[0:3]
	v_mfma_f32_16x16x32_bf16 v[52:55], v[172:175], v[188:191], v[52:55]
	v_mfma_f32_16x16x32_bf16 v[48:51], v[180:183], v[188:191], v[48:51]
	v_mfma_f32_16x16x32_bf16 v[36:39], v[172:175], v[196:199], v[36:39]
	v_mfma_f32_16x16x32_bf16 v[32:35], v[180:183], v[196:199], v[32:35]
	s_barrier
	s_setprio 3
	v_mfma_f32_16x16x32_bf16 v[20:23], v[172:175], v[204:207], v[20:23]
	v_mfma_f32_16x16x32_bf16 v[16:19], v[180:183], v[204:207], v[16:19]
	v_mfma_f32_16x16x32_bf16 v[4:7], v[172:175], v[212:215], v[4:7]
	v_mfma_f32_16x16x32_bf16 v[0:3], v[180:183], v[212:215], v[0:3]
	s_setprio 0
	s_add_i32 s55, s55, 2
	s_add_u32 s53, s53, 0x100
	s_addc_u32 s54, s54, 0
	s_cmpk_gt_u32 s55, 0x55
	s_mov_b64 s[26:27], s[28:29]
	s_cbranch_scc0 .LBB0_307
	v_lshl_add_u32 v142, s51, 8, v144
	v_lshl_or_b32 v140, s52, 8, v146
	v_ashrrev_i32_e32 v143, 31, v142
	v_ashrrev_i32_e32 v141, 31, v140
	v_xor_b32_e32 v212, 16, v150
	v_xor_b32_e32 v213, 32, v150
	v_lshlrev_b32_e32 v212, 2, v212
	v_lshlrev_b32_e32 v213, 2, v213
	v_mov_b32_e32 v152, v142
	v_ashrrev_i32_e32 v153, 31, v152
	v_lshlrev_b64 v[154:155], 11, v[152:153]
	v_lshl_add_u64 v[154:155], v[154:155], 0, v[140:141]
	v_lshl_add_u64 v[156:157], v[154:155], 2, s[0:1]
	global_load_dwordx4 v[164:167], v[156:157], off
	global_load_dwordx4 v[168:171], v[156:157], off offset:64
	global_load_dwordx4 v[172:175], v[156:157], off offset:512
	global_load_dwordx4 v[176:179], v[156:157], off offset:576
	v_add_u32_e32 v152, 16, v142
	v_ashrrev_i32_e32 v153, 31, v152
	v_lshlrev_b64 v[154:155], 11, v[152:153]
	v_lshl_add_u64 v[154:155], v[154:155], 0, v[140:141]
	v_lshl_add_u64 v[156:157], v[154:155], 2, s[0:1]
	global_load_dwordx4 v[180:183], v[156:157], off
	global_load_dwordx4 v[184:187], v[156:157], off offset:64
	global_load_dwordx4 v[188:191], v[156:157], off offset:512
	global_load_dwordx4 v[192:195], v[156:157], off offset:576
	v_add_u32_e32 v152, 32, v142
	v_ashrrev_i32_e32 v153, 31, v152
	v_lshlrev_b64 v[154:155], 11, v[152:153]
	v_lshl_add_u64 v[154:155], v[154:155], 0, v[140:141]
	v_lshl_add_u64 v[156:157], v[154:155], 2, s[0:1]
	global_load_dwordx4 v[196:199], v[156:157], off
	global_load_dwordx4 v[200:203], v[156:157], off offset:64
	global_load_dwordx4 v[204:207], v[156:157], off offset:512
	global_load_dwordx4 v[208:211], v[156:157], off offset:576
	s_and_b64 vcc, exec, s[18:19]
	s_cbranch_vccz .LBB0_310
	s_barrier

; #define PG8_STAGE(bufoff, gbase, voff) do { _Pragma("unroll") for (int _i = 0; _i < 2; ++_i) \
;         __builtin_amdgcn_global_load_lds((const unsigned*)((const char*)(gbase) + (voff)[_i]), (PG8_LAS unsigned*)(lds + (bufoff) + ldsw + _i * 8192), 16, 0, 0); } while (0)
; #define PG8_LDA(dst, b, h) do { _Pragma("unroll") for (int m = 0; m < 4; ++m) _Pragma("unroll") for (int k = 0; k < 2; ++k) dst[m][k] = *(const PG8_LAS bf16x8*)(lds + PG8_SA(b, h) + aoff + m * 2048 + k * 1024); } while (0)
; #define PG8_LDB(dst, b, h) do { _Pragma("unroll") for (int n = 0; n < 2; ++n) _Pragma("unroll") for (int k = 0; k < 2; ++k) dst[n][k] = *(const PG8_LAS bf16x8*)(lds + PG8_SB(b, h) + boff + n * 2048 + k * 1024); } while (0)
; #define PG8_MMA(ai, bj, At, Bt) do { __builtin_amdgcn_s_setprio(1); _Pragma("unroll") for (int m = 0; m < 4; ++m) _Pragma("unroll") for (int n = 0; n < 2; ++n) _Pragma("unroll") for (int k = 0; k < 2; ++k) \
;         acc[ai][bj][m][n] = __builtin_amdgcn_mfma_f32_16x16x32_bf16(Bt[n][k], At[m][k], acc[ai][bj][m][n], 0, 0, 0); __builtin_amdgcn_s_setprio(0); } while (0)
; #define PG8_WAIT_V(n) asm volatile("s_waitcnt vmcnt(" #n ")" ::: "memory")
; #define PG8_WAIT_L(n) asm volatile("s_waitcnt lgkmcnt(" #n ")" ::: "memory")
; #define PG8_BAR __builtin_amdgcn_s_barrier()
; #define PG8_SCHED __builtin_amdgcn_sched_barrier(0)
; template <class Epi, class Sched, bool ALIGN_EPI = false, bool SP2 = false>
; __device__ __forceinline__ void gemm_phase(PG8_LAS unsigned char* lds, const Gemm g, const Sched& S, const Epi& E, int wave_in) {
;     ...
;             const bool last = (t == nt - 2);
;             const char* a1 = cA + (size_t)(t + 1) * kstep;
;             const char* a2 = last ? nA : cA + (size_t)(t + 2) * kstep; const char* b2 = last ? nB : cB + (size_t)(t + 2) * kstep;
;             const char* a3 = a2 + kstep; const char* b3 = b2 + kstep;
;             if (last && has_next) S.a_ready(nxt);
;             if constexpr (SP2) {
;             PG8_LDB(B0, 0, 0); PG8_LDB(B1, 0, 1); PG8_SCHED; PG8_LDA(At, 0, 0); PG8_STAGE(PG8_SA(1, 1), a1 + hstep, voffA);
;             PG8_WAIT_V(8); PG8_WAIT_L(0); PG8_BAR; PG8_MMA(0, 0, At, B0); PG8_MMA(0, 1, At, B1); PG8_BAR; PG8_SCHED;
;             PG8_LDA(At, 0, 1); PG8_STAGE(PG8_SB(0, 0), b2, voffB); PG8_STAGE(PG8_SB(0, 1), b2 + hstep, voffB); PG8_STAGE(PG8_SA(0, 0), a2, voffA);
.LBB0_393:
	ds_read_b128 v[148:151], v159
	ds_read_b128 v[152:155], v159 offset:1024
	ds_read_b128 v[168:171], v159 offset:2048
	ds_read_b128 v[172:175], v159 offset:3072
	ds_read_b128 v[176:179], v160
	ds_read_b128 v[180:183], v160 offset:1024
	ds_read_b128 v[184:187], v160 offset:2048
	ds_read_b128 v[188:191], v160 offset:3072
	s_add_u32 s10, s8, 0xfff80080
	s_addc_u32 s11, s9, -1
	s_cmp_eq_u32 s42, 28
	s_cselect_b32 s39, s5, s11
	s_cselect_b32 s38, s31, s10
	s_cselect_b32 s11, s29, s41
	s_cselect_b32 s10, s33, s40
	v_lshl_add_u64 v[156:157], s[8:9], 0, v[140:141]
	s_add_i32 m0, s48, 0xc000
	ds_read_b128 v[192:195], v161
	ds_read_b128 v[196:199], v161 offset:1024
	ds_read_b128 v[200:203], v161 offset:2048
	ds_read_b128 v[204:207], v161 offset:3072
	ds_read_b128 v[208:211], v161 offset:4096
	ds_read_b128 v[212:215], v161 offset:5120
	ds_read_b128 v[216:219], v161 offset:6144
	ds_read_b128 v[220:223], v161 offset:7168
	global_load_lds_dwordx4 v[156:157], off
	v_lshl_add_u64 v[156:157], s[8:9], 0, v[142:143]
	s_add_i32 m0, s48, 0xe000
	s_nop 0
	global_load_lds_dwordx4 v[156:157], off
	s_waitcnt vmcnt(8)
	s_waitcnt lgkmcnt(0)
	s_barrier
	s_setprio 1
	s_waitcnt lgkmcnt(0)
	v_mfma_f32_16x16x32_bf16 v[124:127], v[148:151], v[192:195], v[124:127]
	v_mfma_f32_16x16x32_bf16 v[120:123], v[168:171], v[192:195], v[120:123]
	v_mfma_f32_16x16x32_bf16 v[108:111], v[148:151], v[200:203], v[108:111]
	v_mfma_f32_16x16x32_bf16 v[104:107], v[168:171], v[200:203], v[104:107]
	v_mfma_f32_16x16x32_bf16 v[92:95], v[148:151], v[208:211], v[92:95]
	v_mfma_f32_16x16x32_bf16 v[88:91], v[168:171], v[208:211], v[88:91]
	v_mfma_f32_16x16x32_bf16 v[76:79], v[148:151], v[216:219], v[76:79]
	v_mfma_f32_16x16x32_bf16 v[72:75], v[168:171], v[216:219], v[72:75]
	v_mfma_f32_16x16x32_bf16 v[124:127], v[152:155], v[196:199], v[124:127]
	v_mfma_f32_16x16x32_bf16 v[120:123], v[172:175], v[196:199], v[120:123]
	v_mfma_f32_16x16x32_bf16 v[108:111], v[152:155], v[204:207], v[108:111]
	v_mfma_f32_16x16x32_bf16 v[104:107], v[172:175], v[204:207], v[104:107]
	v_mfma_f32_16x16x32_bf16 v[92:95], v[152:155], v[212:215], v[92:95]
	v_mfma_f32_16x16x32_bf16 v[88:91], v[172:175], v[212:215], v[88:91]
	v_mfma_f32_16x16x32_bf16 v[76:79], v[152:155], v[220:223], v[76:79]
	v_mfma_f32_16x16x32_bf16 v[72:75], v[172:175], v[220:223], v[72:75]
	s_setprio 0
	s_setprio 1
	v_mfma_f32_16x16x32_bf16 v[116:119], v[176:179], v[192:195], v[116:119]
	v_mfma_f32_16x16x32_bf16 v[112:115], v[184:187], v[192:195], v[112:115]
	v_mfma_f32_16x16x32_bf16 v[100:103], v[176:179], v[200:203], v[100:103]
	v_mfma_f32_16x16x32_bf16 v[96:99], v[184:187], v[200:203], v[96:99]
	v_mfma_f32_16x16x32_bf16 v[84:87], v[176:179], v[208:211], v[84:87]
	v_mfma_f32_16x16x32_bf16 v[80:83], v[184:187], v[208:211], v[80:83]
	v_mfma_f32_16x16x32_bf16 v[68:71], v[176:179], v[216:219], v[68:71]
	v_mfma_f32_16x16x32_bf16 v[64:67], v[184:187], v[216:219], v[64:67]
	v_mfma_f32_16x16x32_bf16 v[116:119], v[180:183], v[196:199], v[116:119]
	v_mfma_f32_16x16x32_bf16 v[112:115], v[188:191], v[196:199], v[112:115]
	v_mfma_f32_16x16x32_bf16 v[100:103], v[180:183], v[204:207], v[100:103]
	v_mfma_f32_16x16x32_bf16 v[96:99], v[188:191], v[204:207], v[96:99]
	s_barrier
	s_setprio 3
	v_mfma_f32_16x16x32_bf16 v[84:87], v[180:183], v[212:215], v[84:87]
	v_mfma_f32_16x16x32_bf16 v[80:83], v[188:191], v[212:215], v[80:83]
	v_mfma_f32_16x16x32_bf16 v[68:71], v[180:183], v[220:223], v[68:71]
	v_mfma_f32_16x16x32_bf16 v[64:67], v[188:191], v[220:223], v[64:67]
	s_setprio 0
	s_add_i32 s43, s61, s21
	v_lshl_add_u64 v[156:157], s[10:11], 0, v[130:131]
	s_mov_b32 m0, s43
	ds_read_b128 v[192:195], v161 offset:16384
	ds_read_b128 v[196:199], v161 offset:17408
	ds_read_b128 v[200:203], v161 offset:18432
	ds_read_b128 v[204:207], v161 offset:19456
	ds_read_b128 v[208:211], v161 offset:20480
	ds_read_b128 v[212:215], v161 offset:21504
	ds_read_b128 v[216:219], v161 offset:22528
	ds_read_b128 v[220:223], v161 offset:23552
	global_load_lds_dwordx4 v[156:157], off
	s_add_i32 m0, s43, 0x2000
	s_add_u32 s44, s10, 0x80000
	v_lshl_add_u64 v[164:165], s[10:11], 0, v[134:135]
	s_addc_u32 s45, s11, 0
	s_add_i32 s43, s62, s21
	global_load_lds_dwordx4 v[164:165], off
	v_lshl_add_u64 v[166:167], s[44:45], 0, v[130:131]
	s_mov_b32 m0, s43
	v_lshl_add_u64 v[224:225], s[38:39], 0, v[132:133]
	global_load_lds_dwordx4 v[166:167], off
	v_lshl_add_u64 v[166:167], s[44:45], 0, v[134:135]
	s_add_i32 m0, s43, 0x2000
	s_nop 0
	global_load_lds_dwordx4 v[166:167], off
	v_lshl_add_u64 v[166:167], s[38:39], 0, v[128:129]
	s_mov_b32 m0, s48
	s_nop 0
	global_load_lds_dwordx4 v[166:167], off
	s_mov_b32 m0, s49
	s_nop 0
	global_load_lds_dwordx4 v[224:225], off
	s_waitcnt vmcnt(8)
	s_waitcnt lgkmcnt(0)
	s_barrier
; #define PG8_STAGE(bufoff, gbase, voff) do { _Pragma("unroll") for (int _i = 0; _i < 2; ++_i) \
;         __builtin_amdgcn_global_load_lds((const unsigned*)((const char*)(gbase) + (voff)[_i]), (PG8_LAS unsigned*)(lds + (bufoff) + ldsw + _i * 8192), 16, 0, 0); } while (0)
; #define PG8_LDA(dst, b, h) do { _Pragma("unroll") for (int m = 0; m < 4; ++m) _Pragma("unroll") for (int k = 0; k < 2; ++k) dst[m][k] = *(const PG8_LAS bf16x8*)(lds + PG8_SA(b, h) + aoff + m * 2048 + k * 1024); } while (0)
; #define PG8_LDB(dst, b, h) do { _Pragma("unroll") for (int n = 0; n < 2; ++n) _Pragma("unroll") for (int k = 0; k < 2; ++k) dst[n][k] = *(const PG8_LAS bf16x8*)(lds + PG8_SB(b, h) + boff + n * 2048 + k * 1024); } while (0)
; #define PG8_MMA(ai, bj, At, Bt) do { __builtin_amdgcn_s_setprio(1); _Pragma("unroll") for (int m = 0; m < 4; ++m) _Pragma("unroll") for (int n = 0; n < 2; ++n) _Pragma("unroll") for (int k = 0; k < 2; ++k) \
;         acc[ai][bj][m][n] = __builtin_amdgcn_mfma_f32_16x16x32_bf16(Bt[n][k], At[m][k], acc[ai][bj][m][n], 0, 0, 0); __builtin_amdgcn_s_setprio(0); } while (0)
; #define PG8_WAIT_V(n) asm volatile("s_waitcnt vmcnt(" #n ")" ::: "memory")
; #define PG8_WAIT_L(n) asm volatile("s_waitcnt lgkmcnt(" #n ")" ::: "memory")
; #define PG8_BAR __builtin_amdgcn_s_barrier()
; #define PG8_SCHED __builtin_amdgcn_sched_barrier(0)
; template <class Epi, class Sched, bool ALIGN_EPI = false, bool SP2 = false>
; __device__ __forceinline__ void gemm_phase(PG8_LAS unsigned char* lds, const Gemm g, const Sched& S, const Epi& E, int wave_in) {
;     ...
;             PG8_LDA(At, 0, 1); PG8_STAGE(PG8_SB(0, 0), b2, voffB); PG8_STAGE(PG8_SB(0, 1), b2 + hstep, voffB); PG8_STAGE(PG8_SA(0, 0), a2, voffA);
;             PG8_WAIT_V(8); PG8_WAIT_L(0); PG8_BAR; PG8_MMA(1, 0, At, B0); PG8_MMA(1, 1, At, B1); PG8_BAR; PG8_SCHED;
;             PG8_LDB(B0, 1, 0); PG8_LDB(B1, 1, 1); PG8_SCHED; PG8_LDA(At, 1, 0); PG8_STAGE(PG8_SA(0, 1), a2 + hstep, voffA);
;             PG8_WAIT_V(8); PG8_WAIT_L(0); PG8_BAR; PG8_MMA(0, 0, At, B0); PG8_MMA(0, 1, At, B1); PG8_BAR; PG8_SCHED;
	s_setprio 1
	s_waitcnt lgkmcnt(0)
	v_mfma_f32_16x16x32_bf16 v[60:63], v[148:151], v[192:195], v[60:63]
	v_mfma_f32_16x16x32_bf16 v[56:59], v[168:171], v[192:195], v[56:59]
	v_mfma_f32_16x16x32_bf16 v[44:47], v[148:151], v[200:203], v[44:47]
	v_mfma_f32_16x16x32_bf16 v[40:43], v[168:171], v[200:203], v[40:43]
	v_mfma_f32_16x16x32_bf16 v[28:31], v[148:151], v[208:211], v[28:31]
	v_mfma_f32_16x16x32_bf16 v[24:27], v[168:171], v[208:211], v[24:27]
	v_mfma_f32_16x16x32_bf16 v[12:15], v[148:151], v[216:219], v[12:15]
	v_mfma_f32_16x16x32_bf16 v[8:11], v[168:171], v[216:219], v[8:11]
	v_mfma_f32_16x16x32_bf16 v[60:63], v[152:155], v[196:199], v[60:63]
	v_mfma_f32_16x16x32_bf16 v[56:59], v[172:175], v[196:199], v[56:59]
	v_mfma_f32_16x16x32_bf16 v[44:47], v[152:155], v[204:207], v[44:47]
	v_mfma_f32_16x16x32_bf16 v[40:43], v[172:175], v[204:207], v[40:43]
	v_mfma_f32_16x16x32_bf16 v[28:31], v[152:155], v[212:215], v[28:31]
	v_mfma_f32_16x16x32_bf16 v[24:27], v[172:175], v[212:215], v[24:27]
	v_mfma_f32_16x16x32_bf16 v[12:15], v[152:155], v[220:223], v[12:15]
	v_mfma_f32_16x16x32_bf16 v[8:11], v[172:175], v[220:223], v[8:11]
	s_setprio 0
	s_setprio 1
	v_mfma_f32_16x16x32_bf16 v[52:55], v[176:179], v[192:195], v[52:55]
	v_mfma_f32_16x16x32_bf16 v[48:51], v[184:187], v[192:195], v[48:51]
	v_mfma_f32_16x16x32_bf16 v[36:39], v[176:179], v[200:203], v[36:39]
	v_mfma_f32_16x16x32_bf16 v[32:35], v[184:187], v[200:203], v[32:35]
	v_mfma_f32_16x16x32_bf16 v[20:23], v[176:179], v[208:211], v[20:23]
	v_mfma_f32_16x16x32_bf16 v[16:19], v[184:187], v[208:211], v[16:19]
	v_mfma_f32_16x16x32_bf16 v[4:7], v[176:179], v[216:219], v[4:7]
	v_mfma_f32_16x16x32_bf16 v[0:3], v[184:187], v[216:219], v[0:3]
	v_mfma_f32_16x16x32_bf16 v[52:55], v[180:183], v[196:199], v[52:55]
	v_mfma_f32_16x16x32_bf16 v[48:51], v[188:191], v[196:199], v[48:51]
	v_mfma_f32_16x16x32_bf16 v[36:39], v[180:183], v[204:207], v[36:39]
	v_mfma_f32_16x16x32_bf16 v[32:35], v[188:191], v[204:207], v[32:35]
	s_barrier
	s_setprio 3
	v_mfma_f32_16x16x32_bf16 v[20:23], v[180:183], v[212:215], v[20:23]
	v_mfma_f32_16x16x32_bf16 v[16:19], v[188:191], v[212:215], v[16:19]
	v_mfma_f32_16x16x32_bf16 v[4:7], v[180:183], v[220:223], v[4:7]
	v_mfma_f32_16x16x32_bf16 v[0:3], v[188:191], v[220:223], v[0:3]
	s_setprio 0
	s_add_i32 s43, 0, 0x18000
	v_add_u32_e32 v136, s43, v158
	s_add_i32 s44, 0, 0x1c000
	ds_read_b128 v[148:151], v136
	ds_read_b128 v[152:155], v136 offset:1024
	ds_read_b128 v[168:171], v136 offset:2048
	ds_read_b128 v[172:175], v136 offset:3072
	v_add_u32_e32 v136, s44, v158
	ds_read_b128 v[176:179], v136
	ds_read_b128 v[180:183], v136 offset:1024
	ds_read_b128 v[184:187], v136 offset:2048
	ds_read_b128 v[188:191], v136 offset:3072
	s_add_u32 s38, s38, 0x80000
	s_addc_u32 s39, s39, 0
	s_mov_b32 m0, s50
	v_lshl_add_u64 v[226:227], s[38:39], 0, v[128:129]
	ds_read_b128 v[192:195], v161 offset:32768
	ds_read_b128 v[196:199], v161 offset:33792
	ds_read_b128 v[200:203], v161 offset:34816
	ds_read_b128 v[204:207], v161 offset:35840
	ds_read_b128 v[208:211], v161 offset:36864
	ds_read_b128 v[212:215], v161 offset:37888
	ds_read_b128 v[216:219], v161 offset:38912
	ds_read_b128 v[220:223], v161 offset:39936
	global_load_lds_dwordx4 v[226:227], off
	v_lshl_add_u64 v[226:227], s[38:39], 0, v[132:133]
	s_mov_b32 m0, s51
	s_nop 0
	global_load_lds_dwordx4 v[226:227], off
	s_waitcnt vmcnt(8)
	s_waitcnt lgkmcnt(0)
	s_barrier
	s_setprio 1
	s_waitcnt lgkmcnt(0)
	v_mfma_f32_16x16x32_bf16 v[124:127], v[148:151], v[192:195], v[124:127]
	v_mfma_f32_16x16x32_bf16 v[120:123], v[168:171], v[192:195], v[120:123]
	v_mfma_f32_16x16x32_bf16 v[108:111], v[148:151], v[200:203], v[108:111]
	v_mfma_f32_16x16x32_bf16 v[104:107], v[168:171], v[200:203], v[104:107]
	v_mfma_f32_16x16x32_bf16 v[92:95], v[148:151], v[208:211], v[92:95]
	v_mfma_f32_16x16x32_bf16 v[88:91], v[168:171], v[208:211], v[88:91]
	v_mfma_f32_16x16x32_bf16 v[76:79], v[148:151], v[216:219], v[76:79]
	v_mfma_f32_16x16x32_bf16 v[72:75], v[168:171], v[216:219], v[72:75]
	v_mfma_f32_16x16x32_bf16 v[124:127], v[152:155], v[196:199], v[124:127]
	v_mfma_f32_16x16x32_bf16 v[120:123], v[172:175], v[196:199], v[120:123]
	v_mfma_f32_16x16x32_bf16 v[108:111], v[152:155], v[204:207], v[108:111]
	v_mfma_f32_16x16x32_bf16 v[104:107], v[172:175], v[204:207], v[104:107]
	v_mfma_f32_16x16x32_bf16 v[92:95], v[152:155], v[212:215], v[92:95]
	v_mfma_f32_16x16x32_bf16 v[88:91], v[172:175], v[212:215], v[88:91]
	v_mfma_f32_16x16x32_bf16 v[76:79], v[152:155], v[220:223], v[76:79]
	v_mfma_f32_16x16x32_bf16 v[72:75], v[172:175], v[220:223], v[72:75]
	s_setprio 0
	s_setprio 1
	v_mfma_f32_16x16x32_bf16 v[116:119], v[176:179], v[192:195], v[116:119]
	v_mfma_f32_16x16x32_bf16 v[112:115], v[184:187], v[192:195], v[112:115]
	v_mfma_f32_16x16x32_bf16 v[100:103], v[176:179], v[200:203], v[100:103]
	v_mfma_f32_16x16x32_bf16 v[96:99], v[184:187], v[200:203], v[96:99]
	v_mfma_f32_16x16x32_bf16 v[84:87], v[176:179], v[208:211], v[84:87]
	v_mfma_f32_16x16x32_bf16 v[80:83], v[184:187], v[208:211], v[80:83]
	v_mfma_f32_16x16x32_bf16 v[68:71], v[176:179], v[216:219], v[68:71]
	v_mfma_f32_16x16x32_bf16 v[64:67], v[184:187], v[216:219], v[64:67]
	v_mfma_f32_16x16x32_bf16 v[116:119], v[180:183], v[196:199], v[116:119]
	v_mfma_f32_16x16x32_bf16 v[112:115], v[188:191], v[196:199], v[112:115]
	v_mfma_f32_16x16x32_bf16 v[100:103], v[180:183], v[204:207], v[100:103]
	v_mfma_f32_16x16x32_bf16 v[96:99], v[188:191], v[204:207], v[96:99]
	s_barrier
; #define PG8_STAGE(bufoff, gbase, voff) do { _Pragma("unroll") for (int _i = 0; _i < 2; ++_i) \
;         __builtin_amdgcn_global_load_lds((const unsigned*)((const char*)(gbase) + (voff)[_i]), (PG8_LAS unsigned*)(lds + (bufoff) + ldsw + _i * 8192), 16, 0, 0); } while (0)
; #define PG8_LDA(dst, b, h) do { _Pragma("unroll") for (int m = 0; m < 4; ++m) _Pragma("unroll") for (int k = 0; k < 2; ++k) dst[m][k] = *(const PG8_LAS bf16x8*)(lds + PG8_SA(b, h) + aoff + m * 2048 + k * 1024); } while (0)
; #define PG8_LDB(dst, b, h) do { _Pragma("unroll") for (int n = 0; n < 2; ++n) _Pragma("unroll") for (int k = 0; k < 2; ++k) dst[n][k] = *(const PG8_LAS bf16x8*)(lds + PG8_SB(b, h) + boff + n * 2048 + k * 1024); } while (0)
; #define PG8_MMA(ai, bj, At, Bt) do { __builtin_amdgcn_s_setprio(1); _Pragma("unroll") for (int m = 0; m < 4; ++m) _Pragma("unroll") for (int n = 0; n < 2; ++n) _Pragma("unroll") for (int k = 0; k < 2; ++k) \
;         acc[ai][bj][m][n] = __builtin_amdgcn_mfma_f32_16x16x32_bf16(Bt[n][k], At[m][k], acc[ai][bj][m][n], 0, 0, 0); __builtin_amdgcn_s_setprio(0); } while (0)
; #define PG8_WAIT_V(n) asm volatile("s_waitcnt vmcnt(" #n ")" ::: "memory")
; #define PG8_WAIT_L(n) asm volatile("s_waitcnt lgkmcnt(" #n ")" ::: "memory")
; #define PG8_BAR __builtin_amdgcn_s_barrier()
; #define PG8_SCHED __builtin_amdgcn_sched_barrier(0)
; template <class Epi, class Sched, bool ALIGN_EPI = false, bool SP2 = false>
; __device__ __forceinline__ void gemm_phase(PG8_LAS unsigned char* lds, const Gemm g, const Sched& S, const Epi& E, int wave_in) {
;     ...
;             PG8_LDB(B0, 1, 0); PG8_LDB(B1, 1, 1); PG8_SCHED; PG8_LDA(At, 1, 0); PG8_STAGE(PG8_SA(0, 1), a2 + hstep, voffA);
;             PG8_WAIT_V(8); PG8_WAIT_L(0); PG8_BAR; PG8_MMA(0, 0, At, B0); PG8_MMA(0, 1, At, B1); PG8_BAR; PG8_SCHED;
;             PG8_LDA(At, 1, 1); PG8_STAGE(PG8_SB(1, 0), b3, voffB); PG8_STAGE(PG8_SB(1, 1), b3 + hstep, voffB); PG8_STAGE(PG8_SA(1, 0), a3, voffA);
;             PG8_WAIT_V(8); PG8_WAIT_L(0); PG8_BAR; PG8_MMA(1, 0, At, B0); PG8_MMA(1, 1, At, B1); PG8_BAR; PG8_SCHED;
	s_setprio 3
	v_mfma_f32_16x16x32_bf16 v[84:87], v[180:183], v[212:215], v[84:87]
	v_mfma_f32_16x16x32_bf16 v[80:83], v[188:191], v[212:215], v[80:83]
	v_mfma_f32_16x16x32_bf16 v[68:71], v[180:183], v[220:223], v[68:71]
	v_mfma_f32_16x16x32_bf16 v[64:67], v[188:191], v[220:223], v[64:67]
	s_setprio 0
	s_add_i32 s38, s43, s21
	v_lshl_add_u64 v[156:157], v[156:157], 0, s[18:19]
	s_mov_b32 m0, s38
	ds_read_b128 v[192:195], v161 offset:49152
	ds_read_b128 v[196:199], v161 offset:50176
	ds_read_b128 v[200:203], v161 offset:51200
	ds_read_b128 v[204:207], v161 offset:52224
	ds_read_b128 v[208:211], v161 offset:53248
	ds_read_b128 v[212:215], v161 offset:54272
	ds_read_b128 v[216:219], v161 offset:55296
	ds_read_b128 v[220:223], v161 offset:56320
	global_load_lds_dwordx4 v[156:157], off
	s_add_i32 m0, s38, 0x2000
	s_add_u32 s10, s10, 0x80080
	v_lshl_add_u64 v[156:157], v[164:165], 0, s[18:19]
	s_addc_u32 s11, s11, 0
	s_add_i32 s38, s44, s21
	global_load_lds_dwordx4 v[156:157], off
	v_lshl_add_u64 v[156:157], s[10:11], 0, v[130:131]
	s_mov_b32 m0, s38
	s_nop 0
	global_load_lds_dwordx4 v[156:157], off
	v_lshl_add_u64 v[156:157], s[10:11], 0, v[134:135]
	s_add_i32 m0, s38, 0x2000
	s_nop 0
	global_load_lds_dwordx4 v[156:157], off
	v_lshl_add_u64 v[156:157], v[166:167], 0, s[18:19]
	s_mov_b32 m0, s55
	s_nop 0
	global_load_lds_dwordx4 v[156:157], off
	v_lshl_add_u64 v[156:157], v[224:225], 0, s[18:19]
	s_mov_b32 m0, s56
	s_nop 0
	global_load_lds_dwordx4 v[156:157], off
	s_waitcnt vmcnt(8)
	s_waitcnt lgkmcnt(0)
	s_barrier
	s_setprio 1
	s_waitcnt lgkmcnt(0)
	v_mfma_f32_16x16x32_bf16 v[60:63], v[148:151], v[192:195], v[60:63]
	v_mfma_f32_16x16x32_bf16 v[56:59], v[168:171], v[192:195], v[56:59]
	v_mfma_f32_16x16x32_bf16 v[44:47], v[148:151], v[200:203], v[44:47]
	v_mfma_f32_16x16x32_bf16 v[40:43], v[168:171], v[200:203], v[40:43]
	v_mfma_f32_16x16x32_bf16 v[28:31], v[148:151], v[208:211], v[28:31]
	v_mfma_f32_16x16x32_bf16 v[24:27], v[168:171], v[208:211], v[24:27]
	v_mfma_f32_16x16x32_bf16 v[12:15], v[148:151], v[216:219], v[12:15]
	v_mfma_f32_16x16x32_bf16 v[8:11], v[168:171], v[216:219], v[8:11]
	v_mfma_f32_16x16x32_bf16 v[60:63], v[152:155], v[196:199], v[60:63]
	v_mfma_f32_16x16x32_bf16 v[56:59], v[172:175], v[196:199], v[56:59]
	v_mfma_f32_16x16x32_bf16 v[44:47], v[152:155], v[204:207], v[44:47]
	v_mfma_f32_16x16x32_bf16 v[40:43], v[172:175], v[204:207], v[40:43]
	v_mfma_f32_16x16x32_bf16 v[28:31], v[152:155], v[212:215], v[28:31]
	v_mfma_f32_16x16x32_bf16 v[24:27], v[172:175], v[212:215], v[24:27]
	v_mfma_f32_16x16x32_bf16 v[12:15], v[152:155], v[220:223], v[12:15]
	v_mfma_f32_16x16x32_bf16 v[8:11], v[172:175], v[220:223], v[8:11]
	s_setprio 0
	s_setprio 1
	v_mfma_f32_16x16x32_bf16 v[52:55], v[176:179], v[192:195], v[52:55]
	v_mfma_f32_16x16x32_bf16 v[48:51], v[184:187], v[192:195], v[48:51]
	v_mfma_f32_16x16x32_bf16 v[36:39], v[176:179], v[200:203], v[36:39]
	v_mfma_f32_16x16x32_bf16 v[32:35], v[184:187], v[200:203], v[32:35]
	v_mfma_f32_16x16x32_bf16 v[20:23], v[176:179], v[208:211], v[20:23]
	v_mfma_f32_16x16x32_bf16 v[16:19], v[184:187], v[208:211], v[16:19]
	v_mfma_f32_16x16x32_bf16 v[4:7], v[176:179], v[216:219], v[4:7]
	v_mfma_f32_16x16x32_bf16 v[0:3], v[184:187], v[216:219], v[0:3]
	v_mfma_f32_16x16x32_bf16 v[52:55], v[180:183], v[196:199], v[52:55]
	v_mfma_f32_16x16x32_bf16 v[48:51], v[188:191], v[196:199], v[48:51]
	v_mfma_f32_16x16x32_bf16 v[36:39], v[180:183], v[204:207], v[36:39]
	v_mfma_f32_16x16x32_bf16 v[32:35], v[188:191], v[204:207], v[32:35]
	s_barrier
	s_setprio 3
	v_mfma_f32_16x16x32_bf16 v[20:23], v[180:183], v[212:215], v[20:23]
	v_mfma_f32_16x16x32_bf16 v[16:19], v[188:191], v[212:215], v[16:19]
	v_mfma_f32_16x16x32_bf16 v[4:7], v[180:183], v[220:223], v[4:7]
	v_mfma_f32_16x16x32_bf16 v[0:3], v[188:191], v[220:223], v[0:3]
	s_setprio 0
	s_add_i32 s42, s42, 2
	s_add_u32 s8, s8, 0x100
	s_addc_u32 s9, s9, 0
	s_add_u32 s40, s40, 0x100
	s_addc_u32 s41, s41, 0
	s_cmp_gt_u32 s42, 29
	s_cbranch_scc0 .LBB0_393
	s_and_b64 vcc, exec, s[24:25]
	s_cbranch_vccz .LBB0_396
	s_barrier

; #define PG8_STAGE(bufoff, gbase, voff) do { _Pragma("unroll") for (int _i = 0; _i < 2; ++_i) \
;         __builtin_amdgcn_global_load_lds((const unsigned*)((const char*)(gbase) + (voff)[_i]), (PG8_LAS unsigned*)(lds + (bufoff) + ldsw + _i * 8192), 16, 0, 0); } while (0)
; #define PG8_LDA(dst, b, h) do { _Pragma("unroll") for (int m = 0; m < 4; ++m) _Pragma("unroll") for (int k = 0; k < 2; ++k) dst[m][k] = *(const PG8_LAS bf16x8*)(lds + PG8_SA(b, h) + aoff + m * 2048 + k * 1024); } while (0)
; #define PG8_LDB(dst, b, h) do { _Pragma("unroll") for (int n = 0; n < 2; ++n) _Pragma("unroll") for (int k = 0; k < 2; ++k) dst[n][k] = *(const PG8_LAS bf16x8*)(lds + PG8_SB(b, h) + boff + n * 2048 + k * 1024); } while (0)
; #define PG8_MMA(ai, bj, At, Bt) do { __builtin_amdgcn_s_setprio(1); _Pragma("unroll") for (int m = 0; m < 4; ++m) _Pragma("unroll") for (int n = 0; n < 2; ++n) _Pragma("unroll") for (int k = 0; k < 2; ++k) \
;         acc[ai][bj][m][n] = __builtin_amdgcn_mfma_f32_16x16x32_bf16(Bt[n][k], At[m][k], acc[ai][bj][m][n], 0, 0, 0); __builtin_amdgcn_s_setprio(0); } while (0)
; #define PG8_WAIT_V(n) asm volatile("s_waitcnt vmcnt(" #n ")" ::: "memory")
; #define PG8_WAIT_L(n) asm volatile("s_waitcnt lgkmcnt(" #n ")" ::: "memory")
; #define PG8_BAR __builtin_amdgcn_s_barrier()
; #define PG8_SCHED __builtin_amdgcn_sched_barrier(0)
; template <class Epi, class Sched, bool ALIGN_EPI = false, bool SP2 = false>
; __device__ __forceinline__ void gemm_phase(PG8_LAS unsigned char* lds, const Gemm g, const Sched& S, const Epi& E, int wave_in) {
;     ...
;             const bool last = (t == nt - 2);
;             const char* a1 = cA + (size_t)(t + 1) * kstep;
;             const char* a2 = last ? nA : cA + (size_t)(t + 2) * kstep; const char* b2 = last ? nB : cB + (size_t)(t + 2) * kstep;
;             const char* a3 = a2 + kstep; const char* b3 = b2 + kstep;
;             if (last && has_next) S.a_ready(nxt);
;             if constexpr (SP2) {
;             PG8_LDB(B0, 0, 0); PG8_LDB(B1, 0, 1); PG8_SCHED; PG8_LDA(At, 0, 0); PG8_STAGE(PG8_SA(1, 1), a1 + hstep, voffA);
;             PG8_WAIT_V(8); PG8_WAIT_L(0); PG8_BAR; PG8_MMA(0, 0, At, B0); PG8_MMA(0, 1, At, B1); PG8_BAR; PG8_SCHED;
;             PG8_LDA(At, 0, 1); PG8_STAGE(PG8_SB(0, 0), b2, voffB); PG8_STAGE(PG8_SB(0, 1), b2 + hstep, voffB); PG8_STAGE(PG8_SA(0, 0), a2, voffA);
.LBB0_845:
	ds_read_b128 v[140:143], v147
	ds_read_b128 v[152:155], v147 offset:1024
	ds_read_b128 v[156:159], v147 offset:2048
	ds_read_b128 v[160:163], v147 offset:3072
	ds_read_b128 v[164:167], v148
	ds_read_b128 v[168:171], v148 offset:1024
	ds_read_b128 v[172:175], v148 offset:2048
	ds_read_b128 v[176:179], v148 offset:3072
	s_add_u32 s26, s24, 0xfff80080
	s_addc_u32 s27, s25, -1
	s_cmp_eq_u32 s48, 28
	s_cselect_b32 s29, s15, s27
	s_cselect_b32 s28, s21, s26
	s_cselect_b32 s27, s13, s47
	s_cselect_b32 s26, s45, s46
	v_lshl_add_u64 v[212:213], s[24:25], 0, v[132:133]
	s_add_i32 m0, s23, 0xc000
	ds_read_b128 v[180:183], v149
	ds_read_b128 v[184:187], v149 offset:1024
	ds_read_b128 v[188:191], v149 offset:2048
	ds_read_b128 v[192:195], v149 offset:3072
	ds_read_b128 v[196:199], v149 offset:4096
	ds_read_b128 v[200:203], v149 offset:5120
	ds_read_b128 v[204:207], v149 offset:6144
	ds_read_b128 v[208:211], v149 offset:7168
	global_load_lds_dwordx4 v[212:213], off
	v_lshl_add_u64 v[212:213], s[24:25], 0, v[134:135]
	s_add_i32 m0, s23, 0xe000
	s_nop 0
	global_load_lds_dwordx4 v[212:213], off
	s_waitcnt vmcnt(8)
	s_waitcnt lgkmcnt(0)
	s_barrier
	s_setprio 1
	s_waitcnt lgkmcnt(0)
	v_mfma_f32_16x16x32_bf16 v[124:127], v[140:143], v[180:183], v[124:127]
	v_mfma_f32_16x16x32_bf16 v[120:123], v[156:159], v[180:183], v[120:123]
	v_mfma_f32_16x16x32_bf16 v[108:111], v[140:143], v[188:191], v[108:111]
	v_mfma_f32_16x16x32_bf16 v[104:107], v[156:159], v[188:191], v[104:107]
	v_mfma_f32_16x16x32_bf16 v[92:95], v[140:143], v[196:199], v[92:95]
	v_mfma_f32_16x16x32_bf16 v[88:91], v[156:159], v[196:199], v[88:91]
	v_mfma_f32_16x16x32_bf16 v[76:79], v[140:143], v[204:207], v[76:79]
	v_mfma_f32_16x16x32_bf16 v[72:75], v[156:159], v[204:207], v[72:75]
	v_mfma_f32_16x16x32_bf16 v[124:127], v[152:155], v[184:187], v[124:127]
	v_mfma_f32_16x16x32_bf16 v[120:123], v[160:163], v[184:187], v[120:123]
	v_mfma_f32_16x16x32_bf16 v[108:111], v[152:155], v[192:195], v[108:111]
	v_mfma_f32_16x16x32_bf16 v[104:107], v[160:163], v[192:195], v[104:107]
	v_mfma_f32_16x16x32_bf16 v[92:95], v[152:155], v[200:203], v[92:95]
	v_mfma_f32_16x16x32_bf16 v[88:91], v[160:163], v[200:203], v[88:91]
	v_mfma_f32_16x16x32_bf16 v[76:79], v[152:155], v[208:211], v[76:79]
	v_mfma_f32_16x16x32_bf16 v[72:75], v[160:163], v[208:211], v[72:75]
	s_setprio 0
	s_setprio 1
	v_mfma_f32_16x16x32_bf16 v[116:119], v[164:167], v[180:183], v[116:119]
	v_mfma_f32_16x16x32_bf16 v[112:115], v[172:175], v[180:183], v[112:115]
	v_mfma_f32_16x16x32_bf16 v[100:103], v[164:167], v[188:191], v[100:103]
	v_mfma_f32_16x16x32_bf16 v[96:99], v[172:175], v[188:191], v[96:99]
	v_mfma_f32_16x16x32_bf16 v[84:87], v[164:167], v[196:199], v[84:87]
	v_mfma_f32_16x16x32_bf16 v[80:83], v[172:175], v[196:199], v[80:83]
	v_mfma_f32_16x16x32_bf16 v[68:71], v[164:167], v[204:207], v[68:71]
	v_mfma_f32_16x16x32_bf16 v[64:67], v[172:175], v[204:207], v[64:67]
	v_mfma_f32_16x16x32_bf16 v[116:119], v[168:171], v[184:187], v[116:119]
	v_mfma_f32_16x16x32_bf16 v[112:115], v[176:179], v[184:187], v[112:115]
	v_mfma_f32_16x16x32_bf16 v[100:103], v[168:171], v[192:195], v[100:103]
	v_mfma_f32_16x16x32_bf16 v[96:99], v[176:179], v[192:195], v[96:99]
	s_barrier
	s_setprio 3
	v_mfma_f32_16x16x32_bf16 v[84:87], v[168:171], v[200:203], v[84:87]
	v_mfma_f32_16x16x32_bf16 v[80:83], v[176:179], v[200:203], v[80:83]
	v_mfma_f32_16x16x32_bf16 v[68:71], v[168:171], v[208:211], v[68:71]
	v_mfma_f32_16x16x32_bf16 v[64:67], v[176:179], v[208:211], v[64:67]
	s_setprio 0
	s_add_i32 s49, s43, s30
	v_lshl_add_u64 v[212:213], s[26:27], 0, v[128:129]
	s_mov_b32 m0, s49
	ds_read_b128 v[180:183], v149 offset:16384
	ds_read_b128 v[184:187], v149 offset:17408
	ds_read_b128 v[188:191], v149 offset:18432
	ds_read_b128 v[192:195], v149 offset:19456
	ds_read_b128 v[196:199], v149 offset:20480
	ds_read_b128 v[200:203], v149 offset:21504
	ds_read_b128 v[204:207], v149 offset:22528
	ds_read_b128 v[208:211], v149 offset:23552
	global_load_lds_dwordx4 v[212:213], off
	s_add_i32 m0, s49, 0x2000
	s_add_u32 s50, s26, 0x80000
	v_lshl_add_u64 v[214:215], s[26:27], 0, v[130:131]
	s_addc_u32 s51, s27, 0
	s_add_i32 s49, s44, s30
	global_load_lds_dwordx4 v[214:215], off
	v_lshl_add_u64 v[216:217], s[50:51], 0, v[128:129]
	s_mov_b32 m0, s49
	v_lshl_add_u64 v[218:219], s[28:29], 0, v[130:131]
	global_load_lds_dwordx4 v[216:217], off
	v_lshl_add_u64 v[216:217], s[50:51], 0, v[130:131]
	s_add_i32 m0, s49, 0x2000
	s_nop 0
	global_load_lds_dwordx4 v[216:217], off
	v_lshl_add_u64 v[216:217], s[28:29], 0, v[128:129]
	s_mov_b32 m0, s23
	s_nop 0
	global_load_lds_dwordx4 v[216:217], off
	s_mov_b32 m0, s34
	s_nop 0
	global_load_lds_dwordx4 v[218:219], off
	s_waitcnt vmcnt(8)
	s_waitcnt lgkmcnt(0)
	s_barrier
; #define PG8_STAGE(bufoff, gbase, voff) do { _Pragma("unroll") for (int _i = 0; _i < 2; ++_i) \
;         __builtin_amdgcn_global_load_lds((const unsigned*)((const char*)(gbase) + (voff)[_i]), (PG8_LAS unsigned*)(lds + (bufoff) + ldsw + _i * 8192), 16, 0, 0); } while (0)
; #define PG8_LDA(dst, b, h) do { _Pragma("unroll") for (int m = 0; m < 4; ++m) _Pragma("unroll") for (int k = 0; k < 2; ++k) dst[m][k] = *(const PG8_LAS bf16x8*)(lds + PG8_SA(b, h) + aoff + m * 2048 + k * 1024); } while (0)
; #define PG8_LDB(dst, b, h) do { _Pragma("unroll") for (int n = 0; n < 2; ++n) _Pragma("unroll") for (int k = 0; k < 2; ++k) dst[n][k] = *(const PG8_LAS bf16x8*)(lds + PG8_SB(b, h) + boff + n * 2048 + k * 1024); } while (0)
; #define PG8_MMA(ai, bj, At, Bt) do { __builtin_amdgcn_s_setprio(1); _Pragma("unroll") for (int m = 0; m < 4; ++m) _Pragma("unroll") for (int n = 0; n < 2; ++n) _Pragma("unroll") for (int k = 0; k < 2; ++k) \
;         acc[ai][bj][m][n] = __builtin_amdgcn_mfma_f32_16x16x32_bf16(Bt[n][k], At[m][k], acc[ai][bj][m][n], 0, 0, 0); __builtin_amdgcn_s_setprio(0); } while (0)
; #define PG8_WAIT_V(n) asm volatile("s_waitcnt vmcnt(" #n ")" ::: "memory")
; #define PG8_WAIT_L(n) asm volatile("s_waitcnt lgkmcnt(" #n ")" ::: "memory")
; #define PG8_BAR __builtin_amdgcn_s_barrier()
; #define PG8_SCHED __builtin_amdgcn_sched_barrier(0)
; template <class Epi, class Sched, bool ALIGN_EPI = false, bool SP2 = false>
; __device__ __forceinline__ void gemm_phase(PG8_LAS unsigned char* lds, const Gemm g, const Sched& S, const Epi& E, int wave_in) {
;     ...
;             PG8_LDA(At, 0, 1); PG8_STAGE(PG8_SB(0, 0), b2, voffB); PG8_STAGE(PG8_SB(0, 1), b2 + hstep, voffB); PG8_STAGE(PG8_SA(0, 0), a2, voffA);
;             PG8_WAIT_V(8); PG8_WAIT_L(0); PG8_BAR; PG8_MMA(1, 0, At, B0); PG8_MMA(1, 1, At, B1); PG8_BAR; PG8_SCHED;
;             PG8_LDB(B0, 1, 0); PG8_LDB(B1, 1, 1); PG8_SCHED; PG8_LDA(At, 1, 0); PG8_STAGE(PG8_SA(0, 1), a2 + hstep, voffA);
;             PG8_WAIT_V(8); PG8_WAIT_L(0); PG8_BAR; PG8_MMA(0, 0, At, B0); PG8_MMA(0, 1, At, B1); PG8_BAR; PG8_SCHED;
	s_setprio 1
	s_waitcnt lgkmcnt(0)
	v_mfma_f32_16x16x32_bf16 v[60:63], v[140:143], v[180:183], v[60:63]
	v_mfma_f32_16x16x32_bf16 v[56:59], v[156:159], v[180:183], v[56:59]
	v_mfma_f32_16x16x32_bf16 v[44:47], v[140:143], v[188:191], v[44:47]
	v_mfma_f32_16x16x32_bf16 v[40:43], v[156:159], v[188:191], v[40:43]
	v_mfma_f32_16x16x32_bf16 v[28:31], v[140:143], v[196:199], v[28:31]
	v_mfma_f32_16x16x32_bf16 v[24:27], v[156:159], v[196:199], v[24:27]
	v_mfma_f32_16x16x32_bf16 v[12:15], v[140:143], v[204:207], v[12:15]
	v_mfma_f32_16x16x32_bf16 v[8:11], v[156:159], v[204:207], v[8:11]
	v_mfma_f32_16x16x32_bf16 v[60:63], v[152:155], v[184:187], v[60:63]
	v_mfma_f32_16x16x32_bf16 v[56:59], v[160:163], v[184:187], v[56:59]
	v_mfma_f32_16x16x32_bf16 v[44:47], v[152:155], v[192:195], v[44:47]
	v_mfma_f32_16x16x32_bf16 v[40:43], v[160:163], v[192:195], v[40:43]
	v_mfma_f32_16x16x32_bf16 v[28:31], v[152:155], v[200:203], v[28:31]
	v_mfma_f32_16x16x32_bf16 v[24:27], v[160:163], v[200:203], v[24:27]
	v_mfma_f32_16x16x32_bf16 v[12:15], v[152:155], v[208:211], v[12:15]
	v_mfma_f32_16x16x32_bf16 v[8:11], v[160:163], v[208:211], v[8:11]
	s_setprio 0
	s_setprio 1
	v_mfma_f32_16x16x32_bf16 v[52:55], v[164:167], v[180:183], v[52:55]
	v_mfma_f32_16x16x32_bf16 v[48:51], v[172:175], v[180:183], v[48:51]
	v_mfma_f32_16x16x32_bf16 v[36:39], v[164:167], v[188:191], v[36:39]
	v_mfma_f32_16x16x32_bf16 v[32:35], v[172:175], v[188:191], v[32:35]
	v_mfma_f32_16x16x32_bf16 v[20:23], v[164:167], v[196:199], v[20:23]
	v_mfma_f32_16x16x32_bf16 v[16:19], v[172:175], v[196:199], v[16:19]
	v_mfma_f32_16x16x32_bf16 v[4:7], v[164:167], v[204:207], v[4:7]
	v_mfma_f32_16x16x32_bf16 v[0:3], v[172:175], v[204:207], v[0:3]
	v_mfma_f32_16x16x32_bf16 v[52:55], v[168:171], v[184:187], v[52:55]
	v_mfma_f32_16x16x32_bf16 v[48:51], v[176:179], v[184:187], v[48:51]
	v_mfma_f32_16x16x32_bf16 v[36:39], v[168:171], v[192:195], v[36:39]
	v_mfma_f32_16x16x32_bf16 v[32:35], v[176:179], v[192:195], v[32:35]
	s_barrier
	s_setprio 3
	v_mfma_f32_16x16x32_bf16 v[20:23], v[168:171], v[200:203], v[20:23]
	v_mfma_f32_16x16x32_bf16 v[16:19], v[176:179], v[200:203], v[16:19]
	v_mfma_f32_16x16x32_bf16 v[4:7], v[168:171], v[208:211], v[4:7]
	v_mfma_f32_16x16x32_bf16 v[0:3], v[176:179], v[208:211], v[0:3]
	s_setprio 0
	s_add_i32 s49, 0, 0x18000
	v_add_u32_e32 v151, s49, v145
	s_add_i32 s50, 0, 0x1c000
	ds_read_b128 v[140:143], v151
	ds_read_b128 v[152:155], v151 offset:1024
	ds_read_b128 v[156:159], v151 offset:2048
	ds_read_b128 v[160:163], v151 offset:3072
	v_add_u32_e32 v151, s50, v145
	ds_read_b128 v[164:167], v151
	ds_read_b128 v[168:171], v151 offset:1024
	ds_read_b128 v[172:175], v151 offset:2048
	ds_read_b128 v[176:179], v151 offset:3072
	s_add_u32 s28, s28, 0x80000
	s_addc_u32 s29, s29, 0
	s_mov_b32 m0, s35
	v_lshl_add_u64 v[220:221], s[28:29], 0, v[128:129]
	ds_read_b128 v[180:183], v149 offset:32768
	ds_read_b128 v[184:187], v149 offset:33792
	ds_read_b128 v[188:191], v149 offset:34816
	ds_read_b128 v[192:195], v149 offset:35840
	ds_read_b128 v[196:199], v149 offset:36864
	ds_read_b128 v[200:203], v149 offset:37888
	ds_read_b128 v[204:207], v149 offset:38912
	ds_read_b128 v[208:211], v149 offset:39936
	global_load_lds_dwordx4 v[220:221], off
	v_lshl_add_u64 v[220:221], s[28:29], 0, v[130:131]
	s_mov_b32 m0, s36
	s_nop 0
	global_load_lds_dwordx4 v[220:221], off
	s_waitcnt vmcnt(8)
	s_waitcnt lgkmcnt(0)
	s_barrier
	s_setprio 1
	s_waitcnt lgkmcnt(0)
	v_mfma_f32_16x16x32_bf16 v[124:127], v[140:143], v[180:183], v[124:127]
	v_mfma_f32_16x16x32_bf16 v[120:123], v[156:159], v[180:183], v[120:123]
	v_mfma_f32_16x16x32_bf16 v[108:111], v[140:143], v[188:191], v[108:111]
	v_mfma_f32_16x16x32_bf16 v[104:107], v[156:159], v[188:191], v[104:107]
	v_mfma_f32_16x16x32_bf16 v[92:95], v[140:143], v[196:199], v[92:95]
	v_mfma_f32_16x16x32_bf16 v[88:91], v[156:159], v[196:199], v[88:91]
	v_mfma_f32_16x16x32_bf16 v[76:79], v[140:143], v[204:207], v[76:79]
	v_mfma_f32_16x16x32_bf16 v[72:75], v[156:159], v[204:207], v[72:75]
	v_mfma_f32_16x16x32_bf16 v[124:127], v[152:155], v[184:187], v[124:127]
	v_mfma_f32_16x16x32_bf16 v[120:123], v[160:163], v[184:187], v[120:123]
	v_mfma_f32_16x16x32_bf16 v[108:111], v[152:155], v[192:195], v[108:111]
	v_mfma_f32_16x16x32_bf16 v[104:107], v[160:163], v[192:195], v[104:107]
	v_mfma_f32_16x16x32_bf16 v[92:95], v[152:155], v[200:203], v[92:95]
	v_mfma_f32_16x16x32_bf16 v[88:91], v[160:163], v[200:203], v[88:91]
	v_mfma_f32_16x16x32_bf16 v[76:79], v[152:155], v[208:211], v[76:79]
	v_mfma_f32_16x16x32_bf16 v[72:75], v[160:163], v[208:211], v[72:75]
	s_setprio 0
	s_setprio 1
	v_mfma_f32_16x16x32_bf16 v[116:119], v[164:167], v[180:183], v[116:119]
	v_mfma_f32_16x16x32_bf16 v[112:115], v[172:175], v[180:183], v[112:115]
	v_mfma_f32_16x16x32_bf16 v[100:103], v[164:167], v[188:191], v[100:103]
	v_mfma_f32_16x16x32_bf16 v[96:99], v[172:175], v[188:191], v[96:99]
	v_mfma_f32_16x16x32_bf16 v[84:87], v[164:167], v[196:199], v[84:87]
	v_mfma_f32_16x16x32_bf16 v[80:83], v[172:175], v[196:199], v[80:83]
	v_mfma_f32_16x16x32_bf16 v[68:71], v[164:167], v[204:207], v[68:71]
	v_mfma_f32_16x16x32_bf16 v[64:67], v[172:175], v[204:207], v[64:67]
	v_mfma_f32_16x16x32_bf16 v[116:119], v[168:171], v[184:187], v[116:119]
	v_mfma_f32_16x16x32_bf16 v[112:115], v[176:179], v[184:187], v[112:115]
	v_mfma_f32_16x16x32_bf16 v[100:103], v[168:171], v[192:195], v[100:103]
	v_mfma_f32_16x16x32_bf16 v[96:99], v[176:179], v[192:195], v[96:99]
	s_barrier
; #define PG8_STAGE(bufoff, gbase, voff) do { _Pragma("unroll") for (int _i = 0; _i < 2; ++_i) \
;         __builtin_amdgcn_global_load_lds((const unsigned*)((const char*)(gbase) + (voff)[_i]), (PG8_LAS unsigned*)(lds + (bufoff) + ldsw + _i * 8192), 16, 0, 0); } while (0)
; #define PG8_LDA(dst, b, h) do { _Pragma("unroll") for (int m = 0; m < 4; ++m) _Pragma("unroll") for (int k = 0; k < 2; ++k) dst[m][k] = *(const PG8_LAS bf16x8*)(lds + PG8_SA(b, h) + aoff + m * 2048 + k * 1024); } while (0)
; #define PG8_LDB(dst, b, h) do { _Pragma("unroll") for (int n = 0; n < 2; ++n) _Pragma("unroll") for (int k = 0; k < 2; ++k) dst[n][k] = *(const PG8_LAS bf16x8*)(lds + PG8_SB(b, h) + boff + n * 2048 + k * 1024); } while (0)
; #define PG8_MMA(ai, bj, At, Bt) do { __builtin_amdgcn_s_setprio(1); _Pragma("unroll") for (int m = 0; m < 4; ++m) _Pragma("unroll") for (int n = 0; n < 2; ++n) _Pragma("unroll") for (int k = 0; k < 2; ++k) \
;         acc[ai][bj][m][n] = __builtin_amdgcn_mfma_f32_16x16x32_bf16(Bt[n][k], At[m][k], acc[ai][bj][m][n], 0, 0, 0); __builtin_amdgcn_s_setprio(0); } while (0)
; #define PG8_WAIT_V(n) asm volatile("s_waitcnt vmcnt(" #n ")" ::: "memory")
; #define PG8_WAIT_L(n) asm volatile("s_waitcnt lgkmcnt(" #n ")" ::: "memory")
; #define PG8_BAR __builtin_amdgcn_s_barrier()
; #define PG8_SCHED __builtin_amdgcn_sched_barrier(0)
; template <class Epi, class Sched, bool ALIGN_EPI = false, bool SP2 = false>
; __device__ __forceinline__ void gemm_phase(PG8_LAS unsigned char* lds, const Gemm g, const Sched& S, const Epi& E, int wave_in) {
;     ...
;             PG8_LDB(B0, 1, 0); PG8_LDB(B1, 1, 1); PG8_SCHED; PG8_LDA(At, 1, 0); PG8_STAGE(PG8_SA(0, 1), a2 + hstep, voffA);
;             PG8_WAIT_V(8); PG8_WAIT_L(0); PG8_BAR; PG8_MMA(0, 0, At, B0); PG8_MMA(0, 1, At, B1); PG8_BAR; PG8_SCHED;
;             PG8_LDA(At, 1, 1); PG8_STAGE(PG8_SB(1, 0), b3, voffB); PG8_STAGE(PG8_SB(1, 1), b3 + hstep, voffB); PG8_STAGE(PG8_SA(1, 0), a3, voffA);
;             PG8_WAIT_V(8); PG8_WAIT_L(0); PG8_BAR; PG8_MMA(1, 0, At, B0); PG8_MMA(1, 1, At, B1); PG8_BAR; PG8_SCHED;
	s_setprio 3
	v_mfma_f32_16x16x32_bf16 v[84:87], v[168:171], v[200:203], v[84:87]
	v_mfma_f32_16x16x32_bf16 v[80:83], v[176:179], v[200:203], v[80:83]
	v_mfma_f32_16x16x32_bf16 v[68:71], v[168:171], v[208:211], v[68:71]
	v_mfma_f32_16x16x32_bf16 v[64:67], v[176:179], v[208:211], v[64:67]
	s_setprio 0
	s_add_i32 s28, s49, s30
	v_lshl_add_u64 v[212:213], v[212:213], 0, s[2:3]
	s_mov_b32 m0, s28
	ds_read_b128 v[180:183], v149 offset:49152
	ds_read_b128 v[184:187], v149 offset:50176
	ds_read_b128 v[188:191], v149 offset:51200
	ds_read_b128 v[192:195], v149 offset:52224
	ds_read_b128 v[196:199], v149 offset:53248
	ds_read_b128 v[200:203], v149 offset:54272
	ds_read_b128 v[204:207], v149 offset:55296
	ds_read_b128 v[208:211], v149 offset:56320
	global_load_lds_dwordx4 v[212:213], off
	s_add_i32 m0, s28, 0x2000
	s_add_u32 s26, s26, 0x80080
	v_lshl_add_u64 v[212:213], v[214:215], 0, s[2:3]
	s_addc_u32 s27, s27, 0
	s_add_i32 s28, s50, s30
	global_load_lds_dwordx4 v[212:213], off
	v_lshl_add_u64 v[212:213], s[26:27], 0, v[128:129]
	s_mov_b32 m0, s28
	s_nop 0
	global_load_lds_dwordx4 v[212:213], off
	v_lshl_add_u64 v[212:213], s[26:27], 0, v[130:131]
	s_add_i32 m0, s28, 0x2000
	s_nop 0
	global_load_lds_dwordx4 v[212:213], off
	v_lshl_add_u64 v[212:213], v[216:217], 0, s[2:3]
	s_mov_b32 m0, s38
	s_nop 0
	global_load_lds_dwordx4 v[212:213], off
	v_lshl_add_u64 v[212:213], v[218:219], 0, s[2:3]
	s_mov_b32 m0, s39
	s_nop 0
	global_load_lds_dwordx4 v[212:213], off
	s_waitcnt vmcnt(8)
	s_waitcnt lgkmcnt(0)
	s_barrier
	s_setprio 1
	s_waitcnt lgkmcnt(0)
	v_mfma_f32_16x16x32_bf16 v[60:63], v[140:143], v[180:183], v[60:63]
	v_mfma_f32_16x16x32_bf16 v[56:59], v[156:159], v[180:183], v[56:59]
	v_mfma_f32_16x16x32_bf16 v[44:47], v[140:143], v[188:191], v[44:47]
	v_mfma_f32_16x16x32_bf16 v[40:43], v[156:159], v[188:191], v[40:43]
	v_mfma_f32_16x16x32_bf16 v[28:31], v[140:143], v[196:199], v[28:31]
	v_mfma_f32_16x16x32_bf16 v[24:27], v[156:159], v[196:199], v[24:27]
	v_mfma_f32_16x16x32_bf16 v[12:15], v[140:143], v[204:207], v[12:15]
	v_mfma_f32_16x16x32_bf16 v[8:11], v[156:159], v[204:207], v[8:11]
	v_mfma_f32_16x16x32_bf16 v[60:63], v[152:155], v[184:187], v[60:63]
	v_mfma_f32_16x16x32_bf16 v[56:59], v[160:163], v[184:187], v[56:59]
	v_mfma_f32_16x16x32_bf16 v[44:47], v[152:155], v[192:195], v[44:47]
	v_mfma_f32_16x16x32_bf16 v[40:43], v[160:163], v[192:195], v[40:43]
	v_mfma_f32_16x16x32_bf16 v[28:31], v[152:155], v[200:203], v[28:31]
	v_mfma_f32_16x16x32_bf16 v[24:27], v[160:163], v[200:203], v[24:27]
	v_mfma_f32_16x16x32_bf16 v[12:15], v[152:155], v[208:211], v[12:15]
	v_mfma_f32_16x16x32_bf16 v[8:11], v[160:163], v[208:211], v[8:11]
	s_setprio 0
	s_setprio 1
	v_mfma_f32_16x16x32_bf16 v[52:55], v[164:167], v[180:183], v[52:55]
	v_mfma_f32_16x16x32_bf16 v[48:51], v[172:175], v[180:183], v[48:51]
	v_mfma_f32_16x16x32_bf16 v[36:39], v[164:167], v[188:191], v[36:39]
	v_mfma_f32_16x16x32_bf16 v[32:35], v[172:175], v[188:191], v[32:35]
	v_mfma_f32_16x16x32_bf16 v[20:23], v[164:167], v[196:199], v[20:23]
	v_mfma_f32_16x16x32_bf16 v[16:19], v[172:175], v[196:199], v[16:19]
	v_mfma_f32_16x16x32_bf16 v[4:7], v[164:167], v[204:207], v[4:7]
	v_mfma_f32_16x16x32_bf16 v[0:3], v[172:175], v[204:207], v[0:3]
	v_mfma_f32_16x16x32_bf16 v[52:55], v[168:171], v[184:187], v[52:55]
	v_mfma_f32_16x16x32_bf16 v[48:51], v[176:179], v[184:187], v[48:51]
	v_mfma_f32_16x16x32_bf16 v[36:39], v[168:171], v[192:195], v[36:39]
	v_mfma_f32_16x16x32_bf16 v[32:35], v[176:179], v[192:195], v[32:35]
	s_barrier
	s_setprio 3
	v_mfma_f32_16x16x32_bf16 v[20:23], v[168:171], v[200:203], v[20:23]
	v_mfma_f32_16x16x32_bf16 v[16:19], v[176:179], v[200:203], v[16:19]
	v_mfma_f32_16x16x32_bf16 v[4:7], v[168:171], v[208:211], v[4:7]
	v_mfma_f32_16x16x32_bf16 v[0:3], v[176:179], v[208:211], v[0:3]
	s_setprio 0
	s_add_i32 s48, s48, 2
	s_add_u32 s24, s24, 0x100
	s_addc_u32 s25, s25, 0
	s_add_u32 s46, s46, 0x100
	s_addc_u32 s47, s47, 0
	s_cmp_gt_u32 s48, 29
	s_cbranch_scc0 .LBB0_845
	s_and_b64 vcc, exec, s[4:5]
	s_cbranch_vccz .LBB0_848
	s_barrier

; #define PG8_STAGE(bufoff, gbase, voff) do { _Pragma("unroll") for (int _i = 0; _i < 2; ++_i) \
;         __builtin_amdgcn_global_load_lds((const unsigned*)((const char*)(gbase) + (voff)[_i]), (PG8_LAS unsigned*)(lds + (bufoff) + ldsw + _i * 8192), 16, 0, 0); } while (0)
; #define PG8_LDA(dst, b, h) do { _Pragma("unroll") for (int m = 0; m < 4; ++m) _Pragma("unroll") for (int k = 0; k < 2; ++k) dst[m][k] = *(const PG8_LAS bf16x8*)(lds + PG8_SA(b, h) + aoff + m * 2048 + k * 1024); } while (0)
; #define PG8_LDB(dst, b, h) do { _Pragma("unroll") for (int n = 0; n < 2; ++n) _Pragma("unroll") for (int k = 0; k < 2; ++k) dst[n][k] = *(const PG8_LAS bf16x8*)(lds + PG8_SB(b, h) + boff + n * 2048 + k * 1024); } while (0)
; #define PG8_MMA(ai, bj, At, Bt) do { __builtin_amdgcn_s_setprio(1); _Pragma("unroll") for (int m = 0; m < 4; ++m) _Pragma("unroll") for (int n = 0; n < 2; ++n) _Pragma("unroll") for (int k = 0; k < 2; ++k) \
;         acc[ai][bj][m][n] = __builtin_amdgcn_mfma_f32_16x16x32_bf16(Bt[n][k], At[m][k], acc[ai][bj][m][n], 0, 0, 0); __builtin_amdgcn_s_setprio(0); } while (0)
; #define PG8_WAIT_V(n) asm volatile("s_waitcnt vmcnt(" #n ")" ::: "memory")
; #define PG8_WAIT_L(n) asm volatile("s_waitcnt lgkmcnt(" #n ")" ::: "memory")
; #define PG8_BAR __builtin_amdgcn_s_barrier()
; #define PG8_SCHED __builtin_amdgcn_sched_barrier(0)
; template <class Epi, class Sched, bool ALIGN_EPI = false, bool SP2 = false>
; __device__ __forceinline__ void gemm_phase(PG8_LAS unsigned char* lds, const Gemm g, const Sched& S, const Epi& E, int wave_in) {
;     ...
;             const bool last = (t == nt - 2);
;             const char* a1 = cA + (size_t)(t + 1) * kstep;
;             const char* a2 = last ? nA : cA + (size_t)(t + 2) * kstep; const char* b2 = last ? nB : cB + (size_t)(t + 2) * kstep;
;             const char* a3 = a2 + kstep; const char* b3 = b2 + kstep;
;             if (last && has_next) S.a_ready(nxt);
;             if constexpr (SP2) {
;             PG8_LDB(B0, 0, 0); PG8_LDB(B1, 0, 1); PG8_SCHED; PG8_LDA(At, 0, 0); PG8_STAGE(PG8_SA(1, 1), a1 + hstep, voffA);
;             PG8_WAIT_V(8); PG8_WAIT_L(0); PG8_BAR; PG8_MMA(0, 0, At, B0); PG8_MMA(0, 1, At, B1); PG8_BAR; PG8_SCHED;
;             PG8_LDA(At, 0, 1); PG8_STAGE(PG8_SB(0, 0), b2, voffB); PG8_STAGE(PG8_SB(0, 1), b2 + hstep, voffB); PG8_STAGE(PG8_SA(0, 0), a2, voffA);
.LBB0_929:
	ds_read_b128 v[144:147], v153
	ds_read_b128 v[158:161], v153 offset:1024
	ds_read_b128 v[162:165], v153 offset:2048
	ds_read_b128 v[166:169], v153 offset:3072
	ds_read_b128 v[170:173], v154
	ds_read_b128 v[174:177], v154 offset:1024
	ds_read_b128 v[178:181], v154 offset:2048
	ds_read_b128 v[182:185], v154 offset:3072
	s_add_u32 s22, s20, 0xfff80080
	s_addc_u32 s23, s21, -1
	s_cmp_eq_u32 s49, 28
	s_cselect_b32 s25, s15, s23
	s_cselect_b32 s24, s45, s22
	s_cselect_b32 s23, s13, s48
	s_cselect_b32 s22, s46, s47
	v_lshl_add_u64 v[148:149], s[20:21], 0, v[136:137]
	s_add_i32 m0, s31, 0xc000
	ds_read_b128 v[186:189], v155
	ds_read_b128 v[190:193], v155 offset:1024
	ds_read_b128 v[194:197], v155 offset:2048
	ds_read_b128 v[198:201], v155 offset:3072
	ds_read_b128 v[202:205], v155 offset:4096
	ds_read_b128 v[206:209], v155 offset:5120
	ds_read_b128 v[210:213], v155 offset:6144
	ds_read_b128 v[214:217], v155 offset:7168
	global_load_lds_dwordx4 v[148:149], off
	v_lshl_add_u64 v[148:149], s[20:21], 0, v[138:139]
	s_add_i32 m0, s31, 0xe000
	s_nop 0
	global_load_lds_dwordx4 v[148:149], off
	s_waitcnt vmcnt(8)
	s_waitcnt lgkmcnt(0)
	s_barrier
	s_setprio 1
	s_waitcnt lgkmcnt(0)
	v_mfma_f32_16x16x32_bf16 v[116:119], v[144:147], v[186:189], v[116:119]
	v_mfma_f32_16x16x32_bf16 v[112:115], v[162:165], v[186:189], v[112:115]
	v_mfma_f32_16x16x32_bf16 v[100:103], v[144:147], v[194:197], v[100:103]
	v_mfma_f32_16x16x32_bf16 v[96:99], v[162:165], v[194:197], v[96:99]
	v_mfma_f32_16x16x32_bf16 v[84:87], v[144:147], v[202:205], v[84:87]
	v_mfma_f32_16x16x32_bf16 v[80:83], v[162:165], v[202:205], v[80:83]
	v_mfma_f32_16x16x32_bf16 v[72:75], v[144:147], v[210:213], v[72:75]
	v_mfma_f32_16x16x32_bf16 v[64:67], v[162:165], v[210:213], v[64:67]
	v_mfma_f32_16x16x32_bf16 v[116:119], v[158:161], v[190:193], v[116:119]
	v_mfma_f32_16x16x32_bf16 v[112:115], v[166:169], v[190:193], v[112:115]
	v_mfma_f32_16x16x32_bf16 v[100:103], v[158:161], v[198:201], v[100:103]
	v_mfma_f32_16x16x32_bf16 v[96:99], v[166:169], v[198:201], v[96:99]
	v_mfma_f32_16x16x32_bf16 v[84:87], v[158:161], v[206:209], v[84:87]
	v_mfma_f32_16x16x32_bf16 v[80:83], v[166:169], v[206:209], v[80:83]
	v_mfma_f32_16x16x32_bf16 v[72:75], v[158:161], v[214:217], v[72:75]
	v_mfma_f32_16x16x32_bf16 v[64:67], v[166:169], v[214:217], v[64:67]
	s_setprio 0
	s_setprio 1
	v_mfma_f32_16x16x32_bf16 v[124:127], v[170:173], v[186:189], v[124:127]
	v_mfma_f32_16x16x32_bf16 v[120:123], v[178:181], v[186:189], v[120:123]
	v_mfma_f32_16x16x32_bf16 v[108:111], v[170:173], v[194:197], v[108:111]
	v_mfma_f32_16x16x32_bf16 v[104:107], v[178:181], v[194:197], v[104:107]
	v_mfma_f32_16x16x32_bf16 v[92:95], v[170:173], v[202:205], v[92:95]
	v_mfma_f32_16x16x32_bf16 v[88:91], v[178:181], v[202:205], v[88:91]
	v_mfma_f32_16x16x32_bf16 v[76:79], v[170:173], v[210:213], v[76:79]
	v_mfma_f32_16x16x32_bf16 v[68:71], v[178:181], v[210:213], v[68:71]
	v_mfma_f32_16x16x32_bf16 v[124:127], v[174:177], v[190:193], v[124:127]
	v_mfma_f32_16x16x32_bf16 v[120:123], v[182:185], v[190:193], v[120:123]
	v_mfma_f32_16x16x32_bf16 v[108:111], v[174:177], v[198:201], v[108:111]
	v_mfma_f32_16x16x32_bf16 v[104:107], v[182:185], v[198:201], v[104:107]
	s_barrier
	s_setprio 3
	v_mfma_f32_16x16x32_bf16 v[92:95], v[174:177], v[206:209], v[92:95]
	v_mfma_f32_16x16x32_bf16 v[88:91], v[182:185], v[206:209], v[88:91]
	v_mfma_f32_16x16x32_bf16 v[76:79], v[174:177], v[214:217], v[76:79]
	v_mfma_f32_16x16x32_bf16 v[68:71], v[182:185], v[214:217], v[68:71]
	s_setprio 0
	s_add_i32 s50, s41, s26
	v_lshl_add_u64 v[148:149], s[22:23], 0, v[132:133]
	s_mov_b32 m0, s50
	ds_read_b128 v[186:189], v155 offset:16384
	ds_read_b128 v[190:193], v155 offset:17408
	ds_read_b128 v[194:197], v155 offset:18432
	ds_read_b128 v[198:201], v155 offset:19456
	ds_read_b128 v[202:205], v155 offset:20480
	ds_read_b128 v[206:209], v155 offset:21504
	ds_read_b128 v[210:213], v155 offset:22528
	ds_read_b128 v[214:217], v155 offset:23552
	global_load_lds_dwordx4 v[148:149], off
	s_add_i32 m0, s50, 0x2000
	s_add_u32 s50, s22, 0x80000
	v_lshl_add_u64 v[218:219], s[22:23], 0, v[128:129]
	s_addc_u32 s51, s23, 0
	s_add_i32 s52, s42, s26
	global_load_lds_dwordx4 v[218:219], off
	v_lshl_add_u64 v[220:221], s[50:51], 0, v[132:133]
	s_mov_b32 m0, s52
	v_lshl_add_u64 v[222:223], s[24:25], 0, v[130:131]
	global_load_lds_dwordx4 v[220:221], off
	v_lshl_add_u64 v[220:221], s[50:51], 0, v[128:129]
	s_add_i32 m0, s52, 0x2000
	s_nop 0
	global_load_lds_dwordx4 v[220:221], off
	v_lshl_add_u64 v[220:221], s[24:25], 0, v[134:135]
	s_mov_b32 m0, s31
	s_nop 0
	global_load_lds_dwordx4 v[220:221], off
	s_mov_b32 m0, s33
	s_nop 0
	global_load_lds_dwordx4 v[222:223], off
	s_waitcnt vmcnt(8)
	s_waitcnt lgkmcnt(0)
	s_barrier
; #define PG8_STAGE(bufoff, gbase, voff) do { _Pragma("unroll") for (int _i = 0; _i < 2; ++_i) \
;         __builtin_amdgcn_global_load_lds((const unsigned*)((const char*)(gbase) + (voff)[_i]), (PG8_LAS unsigned*)(lds + (bufoff) + ldsw + _i * 8192), 16, 0, 0); } while (0)
; #define PG8_LDA(dst, b, h) do { _Pragma("unroll") for (int m = 0; m < 4; ++m) _Pragma("unroll") for (int k = 0; k < 2; ++k) dst[m][k] = *(const PG8_LAS bf16x8*)(lds + PG8_SA(b, h) + aoff + m * 2048 + k * 1024); } while (0)
; #define PG8_LDB(dst, b, h) do { _Pragma("unroll") for (int n = 0; n < 2; ++n) _Pragma("unroll") for (int k = 0; k < 2; ++k) dst[n][k] = *(const PG8_LAS bf16x8*)(lds + PG8_SB(b, h) + boff + n * 2048 + k * 1024); } while (0)
; #define PG8_MMA(ai, bj, At, Bt) do { __builtin_amdgcn_s_setprio(1); _Pragma("unroll") for (int m = 0; m < 4; ++m) _Pragma("unroll") for (int n = 0; n < 2; ++n) _Pragma("unroll") for (int k = 0; k < 2; ++k) \
;         acc[ai][bj][m][n] = __builtin_amdgcn_mfma_f32_16x16x32_bf16(Bt[n][k], At[m][k], acc[ai][bj][m][n], 0, 0, 0); __builtin_amdgcn_s_setprio(0); } while (0)
; #define PG8_WAIT_V(n) asm volatile("s_waitcnt vmcnt(" #n ")" ::: "memory")
; #define PG8_WAIT_L(n) asm volatile("s_waitcnt lgkmcnt(" #n ")" ::: "memory")
; #define PG8_BAR __builtin_amdgcn_s_barrier()
; #define PG8_SCHED __builtin_amdgcn_sched_barrier(0)
; template <class Epi, class Sched, bool ALIGN_EPI = false, bool SP2 = false>
; __device__ __forceinline__ void gemm_phase(PG8_LAS unsigned char* lds, const Gemm g, const Sched& S, const Epi& E, int wave_in) {
;     ...
;             PG8_LDA(At, 0, 1); PG8_STAGE(PG8_SB(0, 0), b2, voffB); PG8_STAGE(PG8_SB(0, 1), b2 + hstep, voffB); PG8_STAGE(PG8_SA(0, 0), a2, voffA);
;             PG8_WAIT_V(8); PG8_WAIT_L(0); PG8_BAR; PG8_MMA(1, 0, At, B0); PG8_MMA(1, 1, At, B1); PG8_BAR; PG8_SCHED;
;             PG8_LDB(B0, 1, 0); PG8_LDB(B1, 1, 1); PG8_SCHED; PG8_LDA(At, 1, 0); PG8_STAGE(PG8_SA(0, 1), a2 + hstep, voffA);
;             PG8_WAIT_V(8); PG8_WAIT_L(0); PG8_BAR; PG8_MMA(0, 0, At, B0); PG8_MMA(0, 1, At, B1); PG8_BAR; PG8_SCHED;
	s_setprio 1
	s_waitcnt lgkmcnt(0)
	v_mfma_f32_16x16x32_bf16 v[52:55], v[144:147], v[186:189], v[52:55]
	v_mfma_f32_16x16x32_bf16 v[48:51], v[162:165], v[186:189], v[48:51]
	v_mfma_f32_16x16x32_bf16 v[36:39], v[144:147], v[194:197], v[36:39]
	v_mfma_f32_16x16x32_bf16 v[32:35], v[162:165], v[194:197], v[32:35]
	v_mfma_f32_16x16x32_bf16 v[20:23], v[144:147], v[202:205], v[20:23]
	v_mfma_f32_16x16x32_bf16 v[16:19], v[162:165], v[202:205], v[16:19]
	v_mfma_f32_16x16x32_bf16 v[4:7], v[144:147], v[210:213], v[4:7]
	v_mfma_f32_16x16x32_bf16 v[0:3], v[162:165], v[210:213], v[0:3]
	v_mfma_f32_16x16x32_bf16 v[52:55], v[158:161], v[190:193], v[52:55]
	v_mfma_f32_16x16x32_bf16 v[48:51], v[166:169], v[190:193], v[48:51]
	v_mfma_f32_16x16x32_bf16 v[36:39], v[158:161], v[198:201], v[36:39]
	v_mfma_f32_16x16x32_bf16 v[32:35], v[166:169], v[198:201], v[32:35]
	v_mfma_f32_16x16x32_bf16 v[20:23], v[158:161], v[206:209], v[20:23]
	v_mfma_f32_16x16x32_bf16 v[16:19], v[166:169], v[206:209], v[16:19]
	v_mfma_f32_16x16x32_bf16 v[4:7], v[158:161], v[214:217], v[4:7]
	v_mfma_f32_16x16x32_bf16 v[0:3], v[166:169], v[214:217], v[0:3]
	s_setprio 0
	s_setprio 1
	v_mfma_f32_16x16x32_bf16 v[60:63], v[170:173], v[186:189], v[60:63]
	v_mfma_f32_16x16x32_bf16 v[56:59], v[178:181], v[186:189], v[56:59]
	v_mfma_f32_16x16x32_bf16 v[44:47], v[170:173], v[194:197], v[44:47]
	v_mfma_f32_16x16x32_bf16 v[40:43], v[178:181], v[194:197], v[40:43]
	v_mfma_f32_16x16x32_bf16 v[28:31], v[170:173], v[202:205], v[28:31]
	v_mfma_f32_16x16x32_bf16 v[24:27], v[178:181], v[202:205], v[24:27]
	v_mfma_f32_16x16x32_bf16 v[12:15], v[170:173], v[210:213], v[12:15]
	v_mfma_f32_16x16x32_bf16 v[8:11], v[178:181], v[210:213], v[8:11]
	v_mfma_f32_16x16x32_bf16 v[60:63], v[174:177], v[190:193], v[60:63]
	v_mfma_f32_16x16x32_bf16 v[56:59], v[182:185], v[190:193], v[56:59]
	v_mfma_f32_16x16x32_bf16 v[44:47], v[174:177], v[198:201], v[44:47]
	v_mfma_f32_16x16x32_bf16 v[40:43], v[182:185], v[198:201], v[40:43]
	s_barrier
	s_setprio 3
	v_mfma_f32_16x16x32_bf16 v[28:31], v[174:177], v[206:209], v[28:31]
	v_mfma_f32_16x16x32_bf16 v[24:27], v[182:185], v[206:209], v[24:27]
	v_mfma_f32_16x16x32_bf16 v[12:15], v[174:177], v[214:217], v[12:15]
	v_mfma_f32_16x16x32_bf16 v[8:11], v[182:185], v[214:217], v[8:11]
	s_setprio 0
	s_add_i32 s50, 0, 0x18000
	s_add_i32 s51, 0, 0x1c000
	v_add_u32_e32 v166, s50, v151
	v_add_u32_e32 v182, s51, v151
	ds_read_b128 v[144:147], v166
	ds_read_b128 v[158:161], v166 offset:1024
	ds_read_b128 v[162:165], v166 offset:2048
	ds_read_b128 v[166:169], v166 offset:3072
	ds_read_b128 v[170:173], v182
	ds_read_b128 v[174:177], v182 offset:1024
	ds_read_b128 v[178:181], v182 offset:2048
	ds_read_b128 v[182:185], v182 offset:3072
	s_add_u32 s24, s24, 0x80000
	s_addc_u32 s25, s25, 0
	s_mov_b32 m0, s34
	v_lshl_add_u64 v[224:225], s[24:25], 0, v[134:135]
	ds_read_b128 v[186:189], v155 offset:32768
	ds_read_b128 v[190:193], v155 offset:33792
	ds_read_b128 v[194:197], v155 offset:34816
	ds_read_b128 v[198:201], v155 offset:35840
	ds_read_b128 v[202:205], v155 offset:36864
	ds_read_b128 v[206:209], v155 offset:37888
	ds_read_b128 v[210:213], v155 offset:38912
	ds_read_b128 v[214:217], v155 offset:39936
	global_load_lds_dwordx4 v[224:225], off
	v_lshl_add_u64 v[224:225], s[24:25], 0, v[130:131]
	s_mov_b32 m0, s35
	s_nop 0
	global_load_lds_dwordx4 v[224:225], off
	s_waitcnt vmcnt(8)
	s_waitcnt lgkmcnt(0)
	s_barrier
	s_setprio 1
	s_waitcnt lgkmcnt(0)
	v_mfma_f32_16x16x32_bf16 v[116:119], v[144:147], v[186:189], v[116:119]
	v_mfma_f32_16x16x32_bf16 v[112:115], v[162:165], v[186:189], v[112:115]
	v_mfma_f32_16x16x32_bf16 v[100:103], v[144:147], v[194:197], v[100:103]
	v_mfma_f32_16x16x32_bf16 v[96:99], v[162:165], v[194:197], v[96:99]
	v_mfma_f32_16x16x32_bf16 v[84:87], v[144:147], v[202:205], v[84:87]
	v_mfma_f32_16x16x32_bf16 v[80:83], v[162:165], v[202:205], v[80:83]
	v_mfma_f32_16x16x32_bf16 v[72:75], v[144:147], v[210:213], v[72:75]
	v_mfma_f32_16x16x32_bf16 v[64:67], v[162:165], v[210:213], v[64:67]
	v_mfma_f32_16x16x32_bf16 v[116:119], v[158:161], v[190:193], v[116:119]
	v_mfma_f32_16x16x32_bf16 v[112:115], v[166:169], v[190:193], v[112:115]
	v_mfma_f32_16x16x32_bf16 v[100:103], v[158:161], v[198:201], v[100:103]
	v_mfma_f32_16x16x32_bf16 v[96:99], v[166:169], v[198:201], v[96:99]
	v_mfma_f32_16x16x32_bf16 v[84:87], v[158:161], v[206:209], v[84:87]
	v_mfma_f32_16x16x32_bf16 v[80:83], v[166:169], v[206:209], v[80:83]
	v_mfma_f32_16x16x32_bf16 v[72:75], v[158:161], v[214:217], v[72:75]
	v_mfma_f32_16x16x32_bf16 v[64:67], v[166:169], v[214:217], v[64:67]
	s_setprio 0
	s_setprio 1
	v_mfma_f32_16x16x32_bf16 v[124:127], v[170:173], v[186:189], v[124:127]
	v_mfma_f32_16x16x32_bf16 v[120:123], v[178:181], v[186:189], v[120:123]
	v_mfma_f32_16x16x32_bf16 v[108:111], v[170:173], v[194:197], v[108:111]
	v_mfma_f32_16x16x32_bf16 v[104:107], v[178:181], v[194:197], v[104:107]
	v_mfma_f32_16x16x32_bf16 v[92:95], v[170:173], v[202:205], v[92:95]
	v_mfma_f32_16x16x32_bf16 v[88:91], v[178:181], v[202:205], v[88:91]
	v_mfma_f32_16x16x32_bf16 v[76:79], v[170:173], v[210:213], v[76:79]
	v_mfma_f32_16x16x32_bf16 v[68:71], v[178:181], v[210:213], v[68:71]
	v_mfma_f32_16x16x32_bf16 v[124:127], v[174:177], v[190:193], v[124:127]
	v_mfma_f32_16x16x32_bf16 v[120:123], v[182:185], v[190:193], v[120:123]
	v_mfma_f32_16x16x32_bf16 v[108:111], v[174:177], v[198:201], v[108:111]
	v_mfma_f32_16x16x32_bf16 v[104:107], v[182:185], v[198:201], v[104:107]
	s_barrier
; #define PG8_STAGE(bufoff, gbase, voff) do { _Pragma("unroll") for (int _i = 0; _i < 2; ++_i) \
;         __builtin_amdgcn_global_load_lds((const unsigned*)((const char*)(gbase) + (voff)[_i]), (PG8_LAS unsigned*)(lds + (bufoff) + ldsw + _i * 8192), 16, 0, 0); } while (0)
; #define PG8_LDA(dst, b, h) do { _Pragma("unroll") for (int m = 0; m < 4; ++m) _Pragma("unroll") for (int k = 0; k < 2; ++k) dst[m][k] = *(const PG8_LAS bf16x8*)(lds + PG8_SA(b, h) + aoff + m * 2048 + k * 1024); } while (0)
; #define PG8_LDB(dst, b, h) do { _Pragma("unroll") for (int n = 0; n < 2; ++n) _Pragma("unroll") for (int k = 0; k < 2; ++k) dst[n][k] = *(const PG8_LAS bf16x8*)(lds + PG8_SB(b, h) + boff + n * 2048 + k * 1024); } while (0)
; #define PG8_MMA(ai, bj, At, Bt) do { __builtin_amdgcn_s_setprio(1); _Pragma("unroll") for (int m = 0; m < 4; ++m) _Pragma("unroll") for (int n = 0; n < 2; ++n) _Pragma("unroll") for (int k = 0; k < 2; ++k) \
;         acc[ai][bj][m][n] = __builtin_amdgcn_mfma_f32_16x16x32_bf16(Bt[n][k], At[m][k], acc[ai][bj][m][n], 0, 0, 0); __builtin_amdgcn_s_setprio(0); } while (0)
; #define PG8_WAIT_V(n) asm volatile("s_waitcnt vmcnt(" #n ")" ::: "memory")
; #define PG8_WAIT_L(n) asm volatile("s_waitcnt lgkmcnt(" #n ")" ::: "memory")
; #define PG8_BAR __builtin_amdgcn_s_barrier()
; #define PG8_SCHED __builtin_amdgcn_sched_barrier(0)
; template <class Epi, class Sched, bool ALIGN_EPI = false, bool SP2 = false>
; __device__ __forceinline__ void gemm_phase(PG8_LAS unsigned char* lds, const Gemm g, const Sched& S, const Epi& E, int wave_in) {
;     ...
;             PG8_LDB(B0, 1, 0); PG8_LDB(B1, 1, 1); PG8_SCHED; PG8_LDA(At, 1, 0); PG8_STAGE(PG8_SA(0, 1), a2 + hstep, voffA);
;             PG8_WAIT_V(8); PG8_WAIT_L(0); PG8_BAR; PG8_MMA(0, 0, At, B0); PG8_MMA(0, 1, At, B1); PG8_BAR; PG8_SCHED;
;             PG8_LDA(At, 1, 1); PG8_STAGE(PG8_SB(1, 0), b3, voffB); PG8_STAGE(PG8_SB(1, 1), b3 + hstep, voffB); PG8_STAGE(PG8_SA(1, 0), a3, voffA);
;             PG8_WAIT_V(8); PG8_WAIT_L(0); PG8_BAR; PG8_MMA(1, 0, At, B0); PG8_MMA(1, 1, At, B1); PG8_BAR; PG8_SCHED;
	s_setprio 3
	v_mfma_f32_16x16x32_bf16 v[92:95], v[174:177], v[206:209], v[92:95]
	v_mfma_f32_16x16x32_bf16 v[88:91], v[182:185], v[206:209], v[88:91]
	v_mfma_f32_16x16x32_bf16 v[76:79], v[174:177], v[214:217], v[76:79]
	v_mfma_f32_16x16x32_bf16 v[68:71], v[182:185], v[214:217], v[68:71]
	s_setprio 0
	s_add_i32 s24, s50, s26
	v_lshl_add_u64 v[148:149], v[148:149], 0, s[2:3]
	s_mov_b32 m0, s24
	ds_read_b128 v[186:189], v155 offset:49152
	ds_read_b128 v[190:193], v155 offset:50176
	ds_read_b128 v[194:197], v155 offset:51200
	ds_read_b128 v[198:201], v155 offset:52224
	ds_read_b128 v[202:205], v155 offset:53248
	ds_read_b128 v[206:209], v155 offset:54272
	ds_read_b128 v[210:213], v155 offset:55296
	ds_read_b128 v[214:217], v155 offset:56320
	global_load_lds_dwordx4 v[148:149], off
	s_add_i32 m0, s24, 0x2000
	s_add_u32 s22, s22, 0x80080
	v_lshl_add_u64 v[148:149], v[218:219], 0, s[2:3]
	s_addc_u32 s23, s23, 0
	s_add_i32 s24, s51, s26
	global_load_lds_dwordx4 v[148:149], off
	v_lshl_add_u64 v[148:149], s[22:23], 0, v[132:133]
	s_mov_b32 m0, s24
	s_nop 0
	global_load_lds_dwordx4 v[148:149], off
	v_lshl_add_u64 v[148:149], s[22:23], 0, v[128:129]
	s_add_i32 m0, s24, 0x2000
	s_nop 0
	global_load_lds_dwordx4 v[148:149], off
	v_lshl_add_u64 v[148:149], v[220:221], 0, s[2:3]
	s_mov_b32 m0, s37
	s_nop 0
	global_load_lds_dwordx4 v[148:149], off
	v_lshl_add_u64 v[148:149], v[222:223], 0, s[2:3]
	s_mov_b32 m0, s38
	s_nop 0
	global_load_lds_dwordx4 v[148:149], off
	s_waitcnt vmcnt(8)
	s_waitcnt lgkmcnt(0)
	s_barrier
	s_setprio 1
	s_waitcnt lgkmcnt(0)
	v_mfma_f32_16x16x32_bf16 v[52:55], v[144:147], v[186:189], v[52:55]
	v_mfma_f32_16x16x32_bf16 v[48:51], v[162:165], v[186:189], v[48:51]
	v_mfma_f32_16x16x32_bf16 v[36:39], v[144:147], v[194:197], v[36:39]
	v_mfma_f32_16x16x32_bf16 v[32:35], v[162:165], v[194:197], v[32:35]
	v_mfma_f32_16x16x32_bf16 v[20:23], v[144:147], v[202:205], v[20:23]
	v_mfma_f32_16x16x32_bf16 v[16:19], v[162:165], v[202:205], v[16:19]
	v_mfma_f32_16x16x32_bf16 v[4:7], v[144:147], v[210:213], v[4:7]
	v_mfma_f32_16x16x32_bf16 v[0:3], v[162:165], v[210:213], v[0:3]
	v_mfma_f32_16x16x32_bf16 v[52:55], v[158:161], v[190:193], v[52:55]
	v_mfma_f32_16x16x32_bf16 v[48:51], v[166:169], v[190:193], v[48:51]
	v_mfma_f32_16x16x32_bf16 v[36:39], v[158:161], v[198:201], v[36:39]
	v_mfma_f32_16x16x32_bf16 v[32:35], v[166:169], v[198:201], v[32:35]
	v_mfma_f32_16x16x32_bf16 v[20:23], v[158:161], v[206:209], v[20:23]
	v_mfma_f32_16x16x32_bf16 v[16:19], v[166:169], v[206:209], v[16:19]
	v_mfma_f32_16x16x32_bf16 v[4:7], v[158:161], v[214:217], v[4:7]
	v_mfma_f32_16x16x32_bf16 v[0:3], v[166:169], v[214:217], v[0:3]
	s_setprio 0
	s_setprio 1
	v_mfma_f32_16x16x32_bf16 v[60:63], v[170:173], v[186:189], v[60:63]
	v_mfma_f32_16x16x32_bf16 v[56:59], v[178:181], v[186:189], v[56:59]
	v_mfma_f32_16x16x32_bf16 v[44:47], v[170:173], v[194:197], v[44:47]
	v_mfma_f32_16x16x32_bf16 v[40:43], v[178:181], v[194:197], v[40:43]
	v_mfma_f32_16x16x32_bf16 v[28:31], v[170:173], v[202:205], v[28:31]
	v_mfma_f32_16x16x32_bf16 v[24:27], v[178:181], v[202:205], v[24:27]
	v_mfma_f32_16x16x32_bf16 v[12:15], v[170:173], v[210:213], v[12:15]
	v_mfma_f32_16x16x32_bf16 v[8:11], v[178:181], v[210:213], v[8:11]
	v_mfma_f32_16x16x32_bf16 v[60:63], v[174:177], v[190:193], v[60:63]
	v_mfma_f32_16x16x32_bf16 v[56:59], v[182:185], v[190:193], v[56:59]
	v_mfma_f32_16x16x32_bf16 v[44:47], v[174:177], v[198:201], v[44:47]
	v_mfma_f32_16x16x32_bf16 v[40:43], v[182:185], v[198:201], v[40:43]
	s_barrier
	s_setprio 3
	v_mfma_f32_16x16x32_bf16 v[28:31], v[174:177], v[206:209], v[28:31]
	v_mfma_f32_16x16x32_bf16 v[24:27], v[182:185], v[206:209], v[24:27]
	v_mfma_f32_16x16x32_bf16 v[12:15], v[174:177], v[214:217], v[12:15]
	v_mfma_f32_16x16x32_bf16 v[8:11], v[182:185], v[214:217], v[8:11]
	s_setprio 0
	s_add_i32 s49, s49, 2
	s_add_u32 s20, s20, 0x100
	s_addc_u32 s21, s21, 0
	s_add_u32 s47, s47, 0x100
	s_addc_u32 s48, s48, 0
	s_cmp_gt_u32 s49, 29
	s_cbranch_scc0 .LBB0_929
	s_and_b64 vcc, exec, s[8:9]
	s_cbranch_vccz .LBB0_932
	s_barrier

; #define PG8_STAGE(bufoff, gbase, voff) do { _Pragma("unroll") for (int _i = 0; _i < 2; ++_i) \
;         __builtin_amdgcn_global_load_lds((const unsigned*)((const char*)(gbase) + (voff)[_i]), (PG8_LAS unsigned*)(lds + (bufoff) + ldsw + _i * 8192), 16, 0, 0); } while (0)
; #define PG8_LDA(dst, b, h) do { _Pragma("unroll") for (int m = 0; m < 4; ++m) _Pragma("unroll") for (int k = 0; k < 2; ++k) dst[m][k] = *(const PG8_LAS bf16x8*)(lds + PG8_SA(b, h) + aoff + m * 2048 + k * 1024); } while (0)
; #define PG8_LDB(dst, b, h) do { _Pragma("unroll") for (int n = 0; n < 2; ++n) _Pragma("unroll") for (int k = 0; k < 2; ++k) dst[n][k] = *(const PG8_LAS bf16x8*)(lds + PG8_SB(b, h) + boff + n * 2048 + k * 1024); } while (0)
; #define PG8_MMA(ai, bj, At, Bt) do { __builtin_amdgcn_s_setprio(1); _Pragma("unroll") for (int m = 0; m < 4; ++m) _Pragma("unroll") for (int n = 0; n < 2; ++n) _Pragma("unroll") for (int k = 0; k < 2; ++k) \
;         acc[ai][bj][m][n] = __builtin_amdgcn_mfma_f32_16x16x32_bf16(Bt[n][k], At[m][k], acc[ai][bj][m][n], 0, 0, 0); __builtin_amdgcn_s_setprio(0); } while (0)
; #define PG8_WAIT_V(n) asm volatile("s_waitcnt vmcnt(" #n ")" ::: "memory")
; #define PG8_WAIT_L(n) asm volatile("s_waitcnt lgkmcnt(" #n ")" ::: "memory")
; #define PG8_BAR __builtin_amdgcn_s_barrier()
; #define PG8_SCHED __builtin_amdgcn_sched_barrier(0)
; template <class Epi, class Sched, bool ALIGN_EPI = false, bool SP2 = false>
; __device__ __forceinline__ void gemm_phase(PG8_LAS unsigned char* lds, const Gemm g, const Sched& S, const Epi& E, int wave_in) {
;     ...
;             const bool last = (t == nt - 2);
;             const char* a1 = cA + (size_t)(t + 1) * kstep;
;             const char* a2 = last ? nA : cA + (size_t)(t + 2) * kstep; const char* b2 = last ? nB : cB + (size_t)(t + 2) * kstep;
;             const char* a3 = a2 + kstep; const char* b3 = b2 + kstep;
;             if (last && has_next) S.a_ready(nxt);
;             if constexpr (SP2) {
;             PG8_LDB(B0, 0, 0); PG8_LDB(B1, 0, 1); PG8_SCHED; PG8_LDA(At, 0, 0); PG8_STAGE(PG8_SA(1, 1), a1 + hstep, voffA);
;             PG8_WAIT_V(8); PG8_WAIT_L(0); PG8_BAR; PG8_MMA(0, 0, At, B0); PG8_MMA(0, 1, At, B1); PG8_BAR; PG8_SCHED;
;             PG8_LDA(At, 0, 1); PG8_STAGE(PG8_SB(0, 0), b2, voffB); PG8_STAGE(PG8_SB(0, 1), b2 + hstep, voffB); PG8_STAGE(PG8_SA(0, 0), a2, voffA);
.LBB0_1009:
	ds_read_b128 v[140:143], v147
	ds_read_b128 v[150:153], v147 offset:1024
	ds_read_b128 v[154:157], v147 offset:2048
	ds_read_b128 v[158:161], v147 offset:3072
	ds_read_b128 v[162:165], v148
	ds_read_b128 v[166:169], v148 offset:1024
	ds_read_b128 v[170:173], v148 offset:2048
	ds_read_b128 v[174:177], v148 offset:3072
	s_add_u32 s18, s16, 0x100
	s_addc_u32 s19, s17, 0
	s_cmpk_eq_i32 s45, 0x54
	s_cselect_b32 s23, s5, s19
	s_cselect_b32 s22, s4, s18
	s_cselect_b32 s21, s15, s44
	s_cselect_b32 s20, s14, s43
	v_lshl_add_u64 v[210:211], s[16:17], 0, v[132:133]
	s_add_i32 m0, s28, 0xc000
	ds_read_b128 v[178:181], v149
	ds_read_b128 v[182:185], v149 offset:1024
	ds_read_b128 v[186:189], v149 offset:2048
	ds_read_b128 v[190:193], v149 offset:3072
	ds_read_b128 v[194:197], v149 offset:4096
	ds_read_b128 v[198:201], v149 offset:5120
	ds_read_b128 v[202:205], v149 offset:6144
	ds_read_b128 v[206:209], v149 offset:7168
	global_load_lds_dwordx4 v[210:211], off
	v_lshl_add_u64 v[210:211], s[16:17], 0, v[134:135]
	s_add_i32 m0, s28, 0xe000
	s_nop 0
	global_load_lds_dwordx4 v[210:211], off
	s_waitcnt vmcnt(8)
	s_waitcnt lgkmcnt(0)
	s_barrier
	s_setprio 1
	s_waitcnt lgkmcnt(0)
	v_mfma_f32_16x16x32_bf16 v[124:127], v[140:143], v[178:181], v[124:127]
	v_mfma_f32_16x16x32_bf16 v[120:123], v[154:157], v[178:181], v[120:123]
	v_mfma_f32_16x16x32_bf16 v[112:115], v[140:143], v[186:189], v[112:115]
	v_mfma_f32_16x16x32_bf16 v[104:107], v[154:157], v[186:189], v[104:107]
	v_mfma_f32_16x16x32_bf16 v[96:99], v[140:143], v[194:197], v[96:99]
	v_mfma_f32_16x16x32_bf16 v[88:91], v[154:157], v[194:197], v[88:91]
	v_mfma_f32_16x16x32_bf16 v[80:83], v[140:143], v[202:205], v[80:83]
	v_mfma_f32_16x16x32_bf16 v[72:75], v[154:157], v[202:205], v[72:75]
	v_mfma_f32_16x16x32_bf16 v[124:127], v[150:153], v[182:185], v[124:127]
	v_mfma_f32_16x16x32_bf16 v[120:123], v[158:161], v[182:185], v[120:123]
	v_mfma_f32_16x16x32_bf16 v[112:115], v[150:153], v[190:193], v[112:115]
	v_mfma_f32_16x16x32_bf16 v[104:107], v[158:161], v[190:193], v[104:107]
	v_mfma_f32_16x16x32_bf16 v[96:99], v[150:153], v[198:201], v[96:99]
	v_mfma_f32_16x16x32_bf16 v[88:91], v[158:161], v[198:201], v[88:91]
	v_mfma_f32_16x16x32_bf16 v[80:83], v[150:153], v[206:209], v[80:83]
	v_mfma_f32_16x16x32_bf16 v[72:75], v[158:161], v[206:209], v[72:75]
	s_setprio 0
	s_setprio 1
	v_mfma_f32_16x16x32_bf16 v[116:119], v[162:165], v[178:181], v[116:119]
	v_mfma_f32_16x16x32_bf16 v[108:111], v[170:173], v[178:181], v[108:111]
	v_mfma_f32_16x16x32_bf16 v[100:103], v[162:165], v[186:189], v[100:103]
	v_mfma_f32_16x16x32_bf16 v[92:95], v[170:173], v[186:189], v[92:95]
	v_mfma_f32_16x16x32_bf16 v[84:87], v[162:165], v[194:197], v[84:87]
	v_mfma_f32_16x16x32_bf16 v[76:79], v[170:173], v[194:197], v[76:79]
	v_mfma_f32_16x16x32_bf16 v[68:71], v[162:165], v[202:205], v[68:71]
	v_mfma_f32_16x16x32_bf16 v[64:67], v[170:173], v[202:205], v[64:67]
	v_mfma_f32_16x16x32_bf16 v[116:119], v[166:169], v[182:185], v[116:119]
	v_mfma_f32_16x16x32_bf16 v[108:111], v[174:177], v[182:185], v[108:111]
	v_mfma_f32_16x16x32_bf16 v[100:103], v[166:169], v[190:193], v[100:103]
	v_mfma_f32_16x16x32_bf16 v[92:95], v[174:177], v[190:193], v[92:95]
	s_barrier
	s_setprio 3
	v_mfma_f32_16x16x32_bf16 v[84:87], v[166:169], v[198:201], v[84:87]
	v_mfma_f32_16x16x32_bf16 v[76:79], v[174:177], v[198:201], v[76:79]
	v_mfma_f32_16x16x32_bf16 v[68:71], v[166:169], v[206:209], v[68:71]
	v_mfma_f32_16x16x32_bf16 v[64:67], v[174:177], v[206:209], v[64:67]
	s_setprio 0
	s_add_i32 s16, s37, s25
	v_lshl_add_u64 v[210:211], s[20:21], 0, v[128:129]
	s_mov_b32 m0, s16
	ds_read_b128 v[178:181], v149 offset:16384
	ds_read_b128 v[182:185], v149 offset:17408
	ds_read_b128 v[186:189], v149 offset:18432
	ds_read_b128 v[190:193], v149 offset:19456
	ds_read_b128 v[194:197], v149 offset:20480
	ds_read_b128 v[198:201], v149 offset:21504
	ds_read_b128 v[202:205], v149 offset:22528
	ds_read_b128 v[206:209], v149 offset:23552
	global_load_lds_dwordx4 v[210:211], off
	s_add_i32 m0, s16, 0x2000
	s_add_u32 s16, s20, 0x160000
	v_lshl_add_u64 v[212:213], s[20:21], 0, v[130:131]
	s_addc_u32 s17, s21, 0
	s_add_i32 s46, s38, s25
	global_load_lds_dwordx4 v[212:213], off
	v_lshl_add_u64 v[214:215], s[16:17], 0, v[128:129]
	s_mov_b32 m0, s46
	v_lshl_add_u64 v[216:217], s[22:23], 0, v[130:131]
	global_load_lds_dwordx4 v[214:215], off
	v_lshl_add_u64 v[214:215], s[16:17], 0, v[130:131]
	s_add_i32 m0, s46, 0x2000
	s_nop 0
	global_load_lds_dwordx4 v[214:215], off
	v_lshl_add_u64 v[214:215], s[22:23], 0, v[128:129]
	s_mov_b32 m0, s28
	s_nop 0
	global_load_lds_dwordx4 v[214:215], off
	s_mov_b32 m0, s29
	s_nop 0
	global_load_lds_dwordx4 v[216:217], off
	s_waitcnt vmcnt(8)
	s_waitcnt lgkmcnt(0)
	s_barrier
; #define PG8_STAGE(bufoff, gbase, voff) do { _Pragma("unroll") for (int _i = 0; _i < 2; ++_i) \
;         __builtin_amdgcn_global_load_lds((const unsigned*)((const char*)(gbase) + (voff)[_i]), (PG8_LAS unsigned*)(lds + (bufoff) + ldsw + _i * 8192), 16, 0, 0); } while (0)
; #define PG8_LDA(dst, b, h) do { _Pragma("unroll") for (int m = 0; m < 4; ++m) _Pragma("unroll") for (int k = 0; k < 2; ++k) dst[m][k] = *(const PG8_LAS bf16x8*)(lds + PG8_SA(b, h) + aoff + m * 2048 + k * 1024); } while (0)
; #define PG8_LDB(dst, b, h) do { _Pragma("unroll") for (int n = 0; n < 2; ++n) _Pragma("unroll") for (int k = 0; k < 2; ++k) dst[n][k] = *(const PG8_LAS bf16x8*)(lds + PG8_SB(b, h) + boff + n * 2048 + k * 1024); } while (0)
; #define PG8_MMA(ai, bj, At, Bt) do { __builtin_amdgcn_s_setprio(1); _Pragma("unroll") for (int m = 0; m < 4; ++m) _Pragma("unroll") for (int n = 0; n < 2; ++n) _Pragma("unroll") for (int k = 0; k < 2; ++k) \
;         acc[ai][bj][m][n] = __builtin_amdgcn_mfma_f32_16x16x32_bf16(Bt[n][k], At[m][k], acc[ai][bj][m][n], 0, 0, 0); __builtin_amdgcn_s_setprio(0); } while (0)
; #define PG8_WAIT_V(n) asm volatile("s_waitcnt vmcnt(" #n ")" ::: "memory")
; #define PG8_WAIT_L(n) asm volatile("s_waitcnt lgkmcnt(" #n ")" ::: "memory")
; #define PG8_BAR __builtin_amdgcn_s_barrier()
; #define PG8_SCHED __builtin_amdgcn_sched_barrier(0)
; template <class Epi, class Sched, bool ALIGN_EPI = false, bool SP2 = false>
; __device__ __forceinline__ void gemm_phase(PG8_LAS unsigned char* lds, const Gemm g, const Sched& S, const Epi& E, int wave_in) {
;     ...
;             PG8_LDA(At, 0, 1); PG8_STAGE(PG8_SB(0, 0), b2, voffB); PG8_STAGE(PG8_SB(0, 1), b2 + hstep, voffB); PG8_STAGE(PG8_SA(0, 0), a2, voffA);
;             PG8_WAIT_V(8); PG8_WAIT_L(0); PG8_BAR; PG8_MMA(1, 0, At, B0); PG8_MMA(1, 1, At, B1); PG8_BAR; PG8_SCHED;
;             PG8_LDB(B0, 1, 0); PG8_LDB(B1, 1, 1); PG8_SCHED; PG8_LDA(At, 1, 0); PG8_STAGE(PG8_SA(0, 1), a2 + hstep, voffA);
;             PG8_WAIT_V(8); PG8_WAIT_L(0); PG8_BAR; PG8_MMA(0, 0, At, B0); PG8_MMA(0, 1, At, B1); PG8_BAR; PG8_SCHED;
	s_setprio 1
	s_waitcnt lgkmcnt(0)
	v_mfma_f32_16x16x32_bf16 v[60:63], v[140:143], v[178:181], v[60:63]
	v_mfma_f32_16x16x32_bf16 v[56:59], v[154:157], v[178:181], v[56:59]
	v_mfma_f32_16x16x32_bf16 v[48:51], v[140:143], v[186:189], v[48:51]
	v_mfma_f32_16x16x32_bf16 v[40:43], v[154:157], v[186:189], v[40:43]
	v_mfma_f32_16x16x32_bf16 v[32:35], v[140:143], v[194:197], v[32:35]
	v_mfma_f32_16x16x32_bf16 v[24:27], v[154:157], v[194:197], v[24:27]
	v_mfma_f32_16x16x32_bf16 v[16:19], v[140:143], v[202:205], v[16:19]
	v_mfma_f32_16x16x32_bf16 v[8:11], v[154:157], v[202:205], v[8:11]
	v_mfma_f32_16x16x32_bf16 v[60:63], v[150:153], v[182:185], v[60:63]
	v_mfma_f32_16x16x32_bf16 v[56:59], v[158:161], v[182:185], v[56:59]
	v_mfma_f32_16x16x32_bf16 v[48:51], v[150:153], v[190:193], v[48:51]
	v_mfma_f32_16x16x32_bf16 v[40:43], v[158:161], v[190:193], v[40:43]
	v_mfma_f32_16x16x32_bf16 v[32:35], v[150:153], v[198:201], v[32:35]
	v_mfma_f32_16x16x32_bf16 v[24:27], v[158:161], v[198:201], v[24:27]
	v_mfma_f32_16x16x32_bf16 v[16:19], v[150:153], v[206:209], v[16:19]
	v_mfma_f32_16x16x32_bf16 v[8:11], v[158:161], v[206:209], v[8:11]
	s_setprio 0
	s_setprio 1
	v_mfma_f32_16x16x32_bf16 v[52:55], v[162:165], v[178:181], v[52:55]
	v_mfma_f32_16x16x32_bf16 v[44:47], v[170:173], v[178:181], v[44:47]
	v_mfma_f32_16x16x32_bf16 v[36:39], v[162:165], v[186:189], v[36:39]
	v_mfma_f32_16x16x32_bf16 v[28:31], v[170:173], v[186:189], v[28:31]
	v_mfma_f32_16x16x32_bf16 v[20:23], v[162:165], v[194:197], v[20:23]
	v_mfma_f32_16x16x32_bf16 v[12:15], v[170:173], v[194:197], v[12:15]
	v_mfma_f32_16x16x32_bf16 v[4:7], v[162:165], v[202:205], v[4:7]
	v_mfma_f32_16x16x32_bf16 v[0:3], v[170:173], v[202:205], v[0:3]
	v_mfma_f32_16x16x32_bf16 v[52:55], v[166:169], v[182:185], v[52:55]
	v_mfma_f32_16x16x32_bf16 v[44:47], v[174:177], v[182:185], v[44:47]
	v_mfma_f32_16x16x32_bf16 v[36:39], v[166:169], v[190:193], v[36:39]
	v_mfma_f32_16x16x32_bf16 v[28:31], v[174:177], v[190:193], v[28:31]
	s_barrier
	s_setprio 3
	v_mfma_f32_16x16x32_bf16 v[20:23], v[166:169], v[198:201], v[20:23]
	v_mfma_f32_16x16x32_bf16 v[12:15], v[174:177], v[198:201], v[12:15]
	v_mfma_f32_16x16x32_bf16 v[4:7], v[166:169], v[206:209], v[4:7]
	v_mfma_f32_16x16x32_bf16 v[0:3], v[174:177], v[206:209], v[0:3]
	s_setprio 0
	s_add_i32 s46, 0, 0x18000
	s_add_i32 s47, 0, 0x1c000
	v_add_u32_e32 v158, s46, v145
	v_add_u32_e32 v174, s47, v145
	ds_read_b128 v[140:143], v158
	ds_read_b128 v[150:153], v158 offset:1024
	ds_read_b128 v[154:157], v158 offset:2048
	ds_read_b128 v[158:161], v158 offset:3072
	ds_read_b128 v[162:165], v174
	ds_read_b128 v[166:169], v174 offset:1024
	ds_read_b128 v[170:173], v174 offset:2048
	ds_read_b128 v[174:177], v174 offset:3072
	s_add_u32 s16, s22, 0x160000
	s_addc_u32 s17, s23, 0
	s_mov_b32 m0, s30
	v_lshl_add_u64 v[218:219], s[16:17], 0, v[128:129]
	ds_read_b128 v[178:181], v149 offset:32768
	ds_read_b128 v[182:185], v149 offset:33792
	ds_read_b128 v[186:189], v149 offset:34816
	ds_read_b128 v[190:193], v149 offset:35840
	ds_read_b128 v[194:197], v149 offset:36864
	ds_read_b128 v[198:201], v149 offset:37888
	ds_read_b128 v[202:205], v149 offset:38912
	ds_read_b128 v[206:209], v149 offset:39936
	global_load_lds_dwordx4 v[218:219], off
	v_lshl_add_u64 v[218:219], s[16:17], 0, v[130:131]
	s_mov_b32 m0, s31
	s_nop 0
	global_load_lds_dwordx4 v[218:219], off
	s_waitcnt vmcnt(8)
	s_waitcnt lgkmcnt(0)
	s_barrier
	s_setprio 1
	s_waitcnt lgkmcnt(0)
	v_mfma_f32_16x16x32_bf16 v[124:127], v[140:143], v[178:181], v[124:127]
	v_mfma_f32_16x16x32_bf16 v[120:123], v[154:157], v[178:181], v[120:123]
	v_mfma_f32_16x16x32_bf16 v[112:115], v[140:143], v[186:189], v[112:115]
	v_mfma_f32_16x16x32_bf16 v[104:107], v[154:157], v[186:189], v[104:107]
	v_mfma_f32_16x16x32_bf16 v[96:99], v[140:143], v[194:197], v[96:99]
	v_mfma_f32_16x16x32_bf16 v[88:91], v[154:157], v[194:197], v[88:91]
	v_mfma_f32_16x16x32_bf16 v[80:83], v[140:143], v[202:205], v[80:83]
	v_mfma_f32_16x16x32_bf16 v[72:75], v[154:157], v[202:205], v[72:75]
	v_mfma_f32_16x16x32_bf16 v[124:127], v[150:153], v[182:185], v[124:127]
	v_mfma_f32_16x16x32_bf16 v[120:123], v[158:161], v[182:185], v[120:123]
	v_mfma_f32_16x16x32_bf16 v[112:115], v[150:153], v[190:193], v[112:115]
	v_mfma_f32_16x16x32_bf16 v[104:107], v[158:161], v[190:193], v[104:107]
	v_mfma_f32_16x16x32_bf16 v[96:99], v[150:153], v[198:201], v[96:99]
	v_mfma_f32_16x16x32_bf16 v[88:91], v[158:161], v[198:201], v[88:91]
	v_mfma_f32_16x16x32_bf16 v[80:83], v[150:153], v[206:209], v[80:83]
	v_mfma_f32_16x16x32_bf16 v[72:75], v[158:161], v[206:209], v[72:75]
	s_setprio 0
	s_setprio 1
	v_mfma_f32_16x16x32_bf16 v[116:119], v[162:165], v[178:181], v[116:119]
	v_mfma_f32_16x16x32_bf16 v[108:111], v[170:173], v[178:181], v[108:111]
	v_mfma_f32_16x16x32_bf16 v[100:103], v[162:165], v[186:189], v[100:103]
	v_mfma_f32_16x16x32_bf16 v[92:95], v[170:173], v[186:189], v[92:95]
	v_mfma_f32_16x16x32_bf16 v[84:87], v[162:165], v[194:197], v[84:87]
	v_mfma_f32_16x16x32_bf16 v[76:79], v[170:173], v[194:197], v[76:79]
	v_mfma_f32_16x16x32_bf16 v[68:71], v[162:165], v[202:205], v[68:71]
	v_mfma_f32_16x16x32_bf16 v[64:67], v[170:173], v[202:205], v[64:67]
	v_mfma_f32_16x16x32_bf16 v[116:119], v[166:169], v[182:185], v[116:119]
	v_mfma_f32_16x16x32_bf16 v[108:111], v[174:177], v[182:185], v[108:111]
	v_mfma_f32_16x16x32_bf16 v[100:103], v[166:169], v[190:193], v[100:103]
	v_mfma_f32_16x16x32_bf16 v[92:95], v[174:177], v[190:193], v[92:95]
	s_barrier
; #define PG8_STAGE(bufoff, gbase, voff) do { _Pragma("unroll") for (int _i = 0; _i < 2; ++_i) \
;         __builtin_amdgcn_global_load_lds((const unsigned*)((const char*)(gbase) + (voff)[_i]), (PG8_LAS unsigned*)(lds + (bufoff) + ldsw + _i * 8192), 16, 0, 0); } while (0)
; #define PG8_LDA(dst, b, h) do { _Pragma("unroll") for (int m = 0; m < 4; ++m) _Pragma("unroll") for (int k = 0; k < 2; ++k) dst[m][k] = *(const PG8_LAS bf16x8*)(lds + PG8_SA(b, h) + aoff + m * 2048 + k * 1024); } while (0)
; #define PG8_LDB(dst, b, h) do { _Pragma("unroll") for (int n = 0; n < 2; ++n) _Pragma("unroll") for (int k = 0; k < 2; ++k) dst[n][k] = *(const PG8_LAS bf16x8*)(lds + PG8_SB(b, h) + boff + n * 2048 + k * 1024); } while (0)
; #define PG8_MMA(ai, bj, At, Bt) do { __builtin_amdgcn_s_setprio(1); _Pragma("unroll") for (int m = 0; m < 4; ++m) _Pragma("unroll") for (int n = 0; n < 2; ++n) _Pragma("unroll") for (int k = 0; k < 2; ++k) \
;         acc[ai][bj][m][n] = __builtin_amdgcn_mfma_f32_16x16x32_bf16(Bt[n][k], At[m][k], acc[ai][bj][m][n], 0, 0, 0); __builtin_amdgcn_s_setprio(0); } while (0)
; #define PG8_WAIT_V(n) asm volatile("s_waitcnt vmcnt(" #n ")" ::: "memory")
; #define PG8_WAIT_L(n) asm volatile("s_waitcnt lgkmcnt(" #n ")" ::: "memory")
; #define PG8_BAR __builtin_amdgcn_s_barrier()
; #define PG8_SCHED __builtin_amdgcn_sched_barrier(0)
; template <class Epi, class Sched, bool ALIGN_EPI = false, bool SP2 = false>
; __device__ __forceinline__ void gemm_phase(PG8_LAS unsigned char* lds, const Gemm g, const Sched& S, const Epi& E, int wave_in) {
;     ...
;             PG8_LDB(B0, 1, 0); PG8_LDB(B1, 1, 1); PG8_SCHED; PG8_LDA(At, 1, 0); PG8_STAGE(PG8_SA(0, 1), a2 + hstep, voffA);
;             PG8_WAIT_V(8); PG8_WAIT_L(0); PG8_BAR; PG8_MMA(0, 0, At, B0); PG8_MMA(0, 1, At, B1); PG8_BAR; PG8_SCHED;
;             PG8_LDA(At, 1, 1); PG8_STAGE(PG8_SB(1, 0), b3, voffB); PG8_STAGE(PG8_SB(1, 1), b3 + hstep, voffB); PG8_STAGE(PG8_SA(1, 0), a3, voffA);
;             PG8_WAIT_V(8); PG8_WAIT_L(0); PG8_BAR; PG8_MMA(1, 0, At, B0); PG8_MMA(1, 1, At, B1); PG8_BAR; PG8_SCHED;
	s_setprio 3
	v_mfma_f32_16x16x32_bf16 v[84:87], v[166:169], v[198:201], v[84:87]
	v_mfma_f32_16x16x32_bf16 v[76:79], v[174:177], v[198:201], v[76:79]
	v_mfma_f32_16x16x32_bf16 v[68:71], v[166:169], v[206:209], v[68:71]
	v_mfma_f32_16x16x32_bf16 v[64:67], v[174:177], v[206:209], v[64:67]
	s_setprio 0
	s_add_i32 s16, s46, s25
	v_lshl_add_u64 v[210:211], v[210:211], 0, s[6:7]
	s_mov_b32 m0, s16
	ds_read_b128 v[178:181], v149 offset:49152
	ds_read_b128 v[182:185], v149 offset:50176
	ds_read_b128 v[186:189], v149 offset:51200
	ds_read_b128 v[190:193], v149 offset:52224
	ds_read_b128 v[194:197], v149 offset:53248
	ds_read_b128 v[198:201], v149 offset:54272
	ds_read_b128 v[202:205], v149 offset:55296
	ds_read_b128 v[206:209], v149 offset:56320
	global_load_lds_dwordx4 v[210:211], off
	s_add_i32 m0, s16, 0x2000
	s_add_u32 s16, s20, 0x160080
	v_lshl_add_u64 v[210:211], v[212:213], 0, s[6:7]
	s_addc_u32 s17, s21, 0
	s_add_i32 s20, s47, s25
	global_load_lds_dwordx4 v[210:211], off
	v_lshl_add_u64 v[210:211], s[16:17], 0, v[128:129]
	s_mov_b32 m0, s20
	s_nop 0
	global_load_lds_dwordx4 v[210:211], off
	v_lshl_add_u64 v[210:211], s[16:17], 0, v[130:131]
	s_add_i32 m0, s20, 0x2000
	s_nop 0
	global_load_lds_dwordx4 v[210:211], off
	v_lshl_add_u64 v[210:211], v[214:215], 0, s[6:7]
	s_mov_b32 m0, s34
	s_nop 0
	global_load_lds_dwordx4 v[210:211], off
	v_lshl_add_u64 v[210:211], v[216:217], 0, s[6:7]
	s_mov_b32 m0, s35
	s_nop 0
	global_load_lds_dwordx4 v[210:211], off
	s_waitcnt vmcnt(8)
	s_waitcnt lgkmcnt(0)
	s_barrier
	s_setprio 1
	s_waitcnt lgkmcnt(0)
	v_mfma_f32_16x16x32_bf16 v[60:63], v[140:143], v[178:181], v[60:63]
	v_mfma_f32_16x16x32_bf16 v[56:59], v[154:157], v[178:181], v[56:59]
	v_mfma_f32_16x16x32_bf16 v[48:51], v[140:143], v[186:189], v[48:51]
	v_mfma_f32_16x16x32_bf16 v[40:43], v[154:157], v[186:189], v[40:43]
	v_mfma_f32_16x16x32_bf16 v[32:35], v[140:143], v[194:197], v[32:35]
	v_mfma_f32_16x16x32_bf16 v[24:27], v[154:157], v[194:197], v[24:27]
	v_mfma_f32_16x16x32_bf16 v[16:19], v[140:143], v[202:205], v[16:19]
	v_mfma_f32_16x16x32_bf16 v[8:11], v[154:157], v[202:205], v[8:11]
	v_mfma_f32_16x16x32_bf16 v[60:63], v[150:153], v[182:185], v[60:63]
	v_mfma_f32_16x16x32_bf16 v[56:59], v[158:161], v[182:185], v[56:59]
	v_mfma_f32_16x16x32_bf16 v[48:51], v[150:153], v[190:193], v[48:51]
	v_mfma_f32_16x16x32_bf16 v[40:43], v[158:161], v[190:193], v[40:43]
	v_mfma_f32_16x16x32_bf16 v[32:35], v[150:153], v[198:201], v[32:35]
	v_mfma_f32_16x16x32_bf16 v[24:27], v[158:161], v[198:201], v[24:27]
	v_mfma_f32_16x16x32_bf16 v[16:19], v[150:153], v[206:209], v[16:19]
	v_mfma_f32_16x16x32_bf16 v[8:11], v[158:161], v[206:209], v[8:11]
	s_setprio 0
	s_setprio 1
	v_mfma_f32_16x16x32_bf16 v[52:55], v[162:165], v[178:181], v[52:55]
	v_mfma_f32_16x16x32_bf16 v[44:47], v[170:173], v[178:181], v[44:47]
	v_mfma_f32_16x16x32_bf16 v[36:39], v[162:165], v[186:189], v[36:39]
	v_mfma_f32_16x16x32_bf16 v[28:31], v[170:173], v[186:189], v[28:31]
	v_mfma_f32_16x16x32_bf16 v[20:23], v[162:165], v[194:197], v[20:23]
	v_mfma_f32_16x16x32_bf16 v[12:15], v[170:173], v[194:197], v[12:15]
	v_mfma_f32_16x16x32_bf16 v[4:7], v[162:165], v[202:205], v[4:7]
	v_mfma_f32_16x16x32_bf16 v[0:3], v[170:173], v[202:205], v[0:3]
	v_mfma_f32_16x16x32_bf16 v[52:55], v[166:169], v[182:185], v[52:55]
	v_mfma_f32_16x16x32_bf16 v[44:47], v[174:177], v[182:185], v[44:47]
	v_mfma_f32_16x16x32_bf16 v[36:39], v[166:169], v[190:193], v[36:39]
	v_mfma_f32_16x16x32_bf16 v[28:31], v[174:177], v[190:193], v[28:31]
	s_barrier
	s_setprio 3
	v_mfma_f32_16x16x32_bf16 v[20:23], v[166:169], v[198:201], v[20:23]
	v_mfma_f32_16x16x32_bf16 v[12:15], v[174:177], v[198:201], v[12:15]
	v_mfma_f32_16x16x32_bf16 v[4:7], v[166:169], v[206:209], v[4:7]
	v_mfma_f32_16x16x32_bf16 v[0:3], v[174:177], v[206:209], v[0:3]
	s_setprio 0
	s_add_i32 s45, s45, 2
	s_add_u32 s43, s43, 0x100
	s_addc_u32 s44, s44, 0
	s_cmpk_gt_u32 s45, 0x55
	s_mov_b64 s[16:17], s[18:19]
	s_cbranch_scc0 .LBB0_1009
	s_and_b64 vcc, exec, s[12:13]
	s_cbranch_vccz .LBB0_1012
	s_barrier
